# stack5 + hot loop headers (GEMM K-loops, attention loops) aligned to 64 bytes
# baseline (speedup 1.0000x reference)
; #define PG8_STAGE(bufoff, gbase, voff) do { _Pragma("unroll") for (int _i = 0; _i < 2; ++_i) \
;         __builtin_amdgcn_global_load_lds((const unsigned*)((const char*)(gbase) + (voff)[_i]), (PG8_LAS unsigned*)(lds + (bufoff) + ldsw + _i * 8192), 16, 0, 0); } while (0)
; #define PG8_LDA(dst, b, h) do { _Pragma("unroll") for (int m = 0; m < 4; ++m) _Pragma("unroll") for (int k = 0; k < 2; ++k) dst[m][k] = *(const PG8_LAS bf16x8*)(lds + PG8_SA(b, h) + aoff + m * 2048 + k * 1024); } while (0)
; #define PG8_LDB(dst, b, h) do { _Pragma("unroll") for (int n = 0; n < 2; ++n) _Pragma("unroll") for (int k = 0; k < 2; ++k) dst[n][k] = *(const PG8_LAS bf16x8*)(lds + PG8_SB(b, h) + boff + n * 2048 + k * 1024); } while (0)
; #define PG8_MMA(ai, bj, At, Bt) do { __builtin_amdgcn_s_setprio(1); _Pragma("unroll") for (int m = 0; m < 4; ++m) _Pragma("unroll") for (int n = 0; n < 2; ++n) _Pragma("unroll") for (int k = 0; k < 2; ++k) \
;         acc[ai][bj][m][n] = __builtin_amdgcn_mfma_f32_16x16x32_bf16(Bt[n][k], At[m][k], acc[ai][bj][m][n], 0, 0, 0); __builtin_amdgcn_s_setprio(0); } while (0)
; template <class Epi, class Sched, bool ALIGN_EPI = false, bool SP2 = false>
; __device__ __forceinline__ void gemm_phase(PG8_LAS unsigned char* lds, const Gemm g, const Sched& S, const Epi& E, int tid_in) {
;     ...
;             if constexpr (SP2) {
;             PG8_LDB(B0, 0, 0); PG8_LDB(B1, 0, 1); PG8_SCHED; PG8_LDA(At, 0, 0); PG8_STAGE(PG8_SA(1, 1), a1 + hstep, voffA);
;             PG8_WAIT_V(8); PG8_WAIT_L(0); PG8_BAR; PG8_MMA(0, 0, At, B0); PG8_MMA(0, 1, At, B1); PG8_BAR; PG8_SCHED;
;             PG8_LDA(At, 0, 1); PG8_STAGE(PG8_SB(0, 0), b2, voffB); PG8_STAGE(PG8_SB(0, 1), b2 + hstep, voffB); PG8_STAGE(PG8_SA(0, 0), a2, voffA);
;             PG8_WAIT_V(8); PG8_WAIT_L(0); PG8_BAR; PG8_MMA(1, 0, At, B0); PG8_MMA(1, 1, At, B1); PG8_BAR; PG8_SCHED;
;             PG8_LDB(B0, 1, 0); PG8_LDB(B1, 1, 1); PG8_SCHED; PG8_LDA(At, 1, 0); PG8_STAGE(PG8_SA(0, 1), a2 + hstep, voffA);
;             PG8_WAIT_V(8); PG8_WAIT_L(0); PG8_BAR; PG8_MMA(0, 0, At, B0); PG8_MMA(0, 1, At, B1); PG8_BAR; PG8_SCHED;
;             PG8_LDA(At, 1, 1); PG8_STAGE(PG8_SB(1, 0), b3, voffB); PG8_STAGE(PG8_SB(1, 1), b3 + hstep, voffB); PG8_STAGE(PG8_SA(1, 0), a3, voffA);
;             PG8_WAIT_V(8); PG8_WAIT_L(0); PG8_BAR; PG8_MMA(1, 0, At, B0); PG8_MMA(1, 1, At, B1); PG8_BAR; PG8_SCHED;
.LBB0_74:
	s_add_u32 s30, s24, 0x100
	s_addc_u32 s31, s25, 0
	s_mov_b32 s44, -2
	s_add_u32 s24, s22, 0x100
	s_addc_u32 s25, s23, 0
	s_add_i32 s45, 0, 0x10000
	s_cmp_eq_u32 s44, 40
	s_cselect_b32 s29, s61, s25
	s_cselect_b32 s28, s60, s24
	s_cselect_b32 s27, s21, s31
	s_cselect_b32 s26, s20, s30
	s_add_i32 s48, 0, 0x14000
	v_add_u32_e32 v152, s45, v159
	v_add_u32_e32 v156, s48, v159
	ds_read_b128 v[130:133], v152
	ds_read_b128 v[134:137], v152 offset:1024
	ds_read_b128 v[148:151], v152 offset:2048
	ds_read_b128 v[152:155], v152 offset:3072
	ds_read_b128 v[180:183], v156
	ds_read_b128 v[184:187], v156 offset:1024
	ds_read_b128 v[188:191], v156 offset:2048
	ds_read_b128 v[192:195], v156 offset:3072
	v_lshl_add_u64 v[156:157], s[22:23], 0, v[144:145]
	s_add_i32 m0, s62, 0xc000
	ds_read_b128 v[196:199], v178
	ds_read_b128 v[200:203], v178 offset:1024
	ds_read_b128 v[204:207], v178 offset:2048
	ds_read_b128 v[208:211], v178 offset:3072
	ds_read_b128 v[212:215], v178 offset:4096
	ds_read_b128 v[216:219], v178 offset:5120
	ds_read_b128 v[220:223], v178 offset:6144
	ds_read_b128 v[242:245], v178 offset:7168
	global_load_lds_dwordx4 v[156:157], off
	v_lshl_add_u64 v[156:157], s[22:23], 0, v[146:147]
	s_add_i32 m0, s62, 0xe000
	s_nop 0
	global_load_lds_dwordx4 v[156:157], off
	s_waitcnt vmcnt(8)
	s_waitcnt lgkmcnt(0)
	s_barrier
	s_setprio 1
	s_waitcnt lgkmcnt(0)
	v_mfma_f32_16x16x32_bf16 v[126:129], v[130:133], v[196:199], 0
	v_mfma_f32_16x16x32_bf16 v[122:125], v[148:151], v[196:199], 0
	v_mfma_f32_16x16x32_bf16 v[110:113], v[130:133], v[204:207], 0
	v_mfma_f32_16x16x32_bf16 v[106:109], v[148:151], v[204:207], 0
	v_mfma_f32_16x16x32_bf16 v[94:97], v[130:133], v[212:215], 0
	v_mfma_f32_16x16x32_bf16 v[90:93], v[148:151], v[212:215], 0
	v_mfma_f32_16x16x32_bf16 v[78:81], v[130:133], v[220:223], 0
	v_mfma_f32_16x16x32_bf16 v[74:77], v[148:151], v[220:223], 0
	v_mfma_f32_16x16x32_bf16 v[126:129], v[134:137], v[200:203], v[126:129]
	v_mfma_f32_16x16x32_bf16 v[122:125], v[152:155], v[200:203], v[122:125]
	v_mfma_f32_16x16x32_bf16 v[110:113], v[134:137], v[208:211], v[110:113]
	v_mfma_f32_16x16x32_bf16 v[106:109], v[152:155], v[208:211], v[106:109]
	v_mfma_f32_16x16x32_bf16 v[94:97], v[134:137], v[216:219], v[94:97]
	v_mfma_f32_16x16x32_bf16 v[90:93], v[152:155], v[216:219], v[90:93]
	v_mfma_f32_16x16x32_bf16 v[78:81], v[134:137], v[242:245], v[78:81]
	v_mfma_f32_16x16x32_bf16 v[74:77], v[152:155], v[242:245], v[74:77]
	v_mfma_f32_16x16x32_bf16 v[118:121], v[180:183], v[196:199], 0
	v_mfma_f32_16x16x32_bf16 v[114:117], v[188:191], v[196:199], 0
	v_mfma_f32_16x16x32_bf16 v[102:105], v[180:183], v[204:207], 0
	v_mfma_f32_16x16x32_bf16 v[98:101], v[188:191], v[204:207], 0
	v_mfma_f32_16x16x32_bf16 v[86:89], v[180:183], v[212:215], 0
	v_mfma_f32_16x16x32_bf16 v[82:85], v[188:191], v[212:215], 0
	v_mfma_f32_16x16x32_bf16 v[70:73], v[180:183], v[220:223], 0
	v_mfma_f32_16x16x32_bf16 v[66:69], v[188:191], v[220:223], 0
	v_mfma_f32_16x16x32_bf16 v[118:121], v[184:187], v[200:203], v[118:121]
	v_mfma_f32_16x16x32_bf16 v[114:117], v[192:195], v[200:203], v[114:117]
	v_mfma_f32_16x16x32_bf16 v[102:105], v[184:187], v[208:211], v[102:105]
	v_mfma_f32_16x16x32_bf16 v[98:101], v[192:195], v[208:211], v[98:101]
	v_mfma_f32_16x16x32_bf16 v[86:89], v[184:187], v[216:219], v[86:89]
	v_mfma_f32_16x16x32_bf16 v[82:85], v[192:195], v[216:219], v[82:85]
	v_mfma_f32_16x16x32_bf16 v[70:73], v[184:187], v[242:245], v[70:73]
	v_mfma_f32_16x16x32_bf16 v[66:69], v[192:195], v[242:245], v[66:69]
	s_setprio 0
	s_barrier
	s_add_i32 s22, s45, s37
	v_lshl_add_u64 v[156:157], s[26:27], 0, v[64:65]
	s_mov_b32 m0, s22
	ds_read_b128 v[196:199], v178 offset:16384
	ds_read_b128 v[200:203], v178 offset:17408
	ds_read_b128 v[204:207], v178 offset:18432
	ds_read_b128 v[208:211], v178 offset:19456
	ds_read_b128 v[212:215], v178 offset:20480
	ds_read_b128 v[216:219], v178 offset:21504
	ds_read_b128 v[220:223], v178 offset:22528
	ds_read_b128 v[242:245], v178 offset:23552
	global_load_lds_dwordx4 v64, s[26:27]
	s_add_i32 m0, s22, 0x2000
	s_add_u32 s22, s26, 0xb0000
	v_lshl_add_u64 v[172:173], s[26:27], 0, v[142:143]
	s_addc_u32 s23, s27, 0
	s_add_i32 s45, s48, s37
	global_load_lds_dwordx4 v142, s[26:27]
	s_mov_b32 m0, s45
	v_lshl_add_u64 v[232:233], s[28:29], 0, v[140:141]
	global_load_lds_dwordx4 v64, s[22:23]
	s_add_i32 m0, s45, 0x2000
	s_nop 0
	global_load_lds_dwordx4 v142, s[22:23]
	v_lshl_add_u64 v[224:225], s[28:29], 0, v[138:139]
	s_mov_b32 m0, s62
	s_nop 0
	global_load_lds_dwordx4 v138, s[28:29]
	s_mov_b32 m0, s63
	s_nop 0
	global_load_lds_dwordx4 v140, s[28:29]
	s_waitcnt vmcnt(8)
	s_waitcnt lgkmcnt(0)
	s_barrier
; #define PG8_STAGE(bufoff, gbase, voff) do { _Pragma("unroll") for (int _i = 0; _i < 2; ++_i) \
;         __builtin_amdgcn_global_load_lds((const unsigned*)((const char*)(gbase) + (voff)[_i]), (PG8_LAS unsigned*)(lds + (bufoff) + ldsw + _i * 8192), 16, 0, 0); } while (0)
; #define PG8_LDA(dst, b, h) do { _Pragma("unroll") for (int m = 0; m < 4; ++m) _Pragma("unroll") for (int k = 0; k < 2; ++k) dst[m][k] = *(const PG8_LAS bf16x8*)(lds + PG8_SA(b, h) + aoff + m * 2048 + k * 1024); } while (0)
; #define PG8_LDB(dst, b, h) do { _Pragma("unroll") for (int n = 0; n < 2; ++n) _Pragma("unroll") for (int k = 0; k < 2; ++k) dst[n][k] = *(const PG8_LAS bf16x8*)(lds + PG8_SB(b, h) + boff + n * 2048 + k * 1024); } while (0)
; #define PG8_MMA(ai, bj, At, Bt) do { __builtin_amdgcn_s_setprio(1); _Pragma("unroll") for (int m = 0; m < 4; ++m) _Pragma("unroll") for (int n = 0; n < 2; ++n) _Pragma("unroll") for (int k = 0; k < 2; ++k) \
;         acc[ai][bj][m][n] = __builtin_amdgcn_mfma_f32_16x16x32_bf16(Bt[n][k], At[m][k], acc[ai][bj][m][n], 0, 0, 0); __builtin_amdgcn_s_setprio(0); } while (0)
; template <class Epi, class Sched, bool ALIGN_EPI = false, bool SP2 = false>
; __device__ __forceinline__ void gemm_phase(PG8_LAS unsigned char* lds, const Gemm g, const Sched& S, const Epi& E, int tid_in) {
;     ...
;             if constexpr (SP2) {
;             PG8_LDB(B0, 0, 0); PG8_LDB(B1, 0, 1); PG8_SCHED; PG8_LDA(At, 0, 0); PG8_STAGE(PG8_SA(1, 1), a1 + hstep, voffA);
;             PG8_WAIT_V(8); PG8_WAIT_L(0); PG8_BAR; PG8_MMA(0, 0, At, B0); PG8_MMA(0, 1, At, B1); PG8_BAR; PG8_SCHED;
;             PG8_LDA(At, 0, 1); PG8_STAGE(PG8_SB(0, 0), b2, voffB); PG8_STAGE(PG8_SB(0, 1), b2 + hstep, voffB); PG8_STAGE(PG8_SA(0, 0), a2, voffA);
;             PG8_WAIT_V(8); PG8_WAIT_L(0); PG8_BAR; PG8_MMA(1, 0, At, B0); PG8_MMA(1, 1, At, B1); PG8_BAR; PG8_SCHED;
;             PG8_LDB(B0, 1, 0); PG8_LDB(B1, 1, 1); PG8_SCHED; PG8_LDA(At, 1, 0); PG8_STAGE(PG8_SA(0, 1), a2 + hstep, voffA);
;             PG8_WAIT_V(8); PG8_WAIT_L(0); PG8_BAR; PG8_MMA(0, 0, At, B0); PG8_MMA(0, 1, At, B1); PG8_BAR; PG8_SCHED;
;             PG8_LDA(At, 1, 1); PG8_STAGE(PG8_SB(1, 0), b3, voffB); PG8_STAGE(PG8_SB(1, 1), b3 + hstep, voffB); PG8_STAGE(PG8_SA(1, 0), a3, voffA);
;             PG8_WAIT_V(8); PG8_WAIT_L(0); PG8_BAR; PG8_MMA(1, 0, At, B0); PG8_MMA(1, 1, At, B1); PG8_BAR; PG8_SCHED;
	s_setprio 1
	s_waitcnt lgkmcnt(0)
	v_mfma_f32_16x16x32_bf16 v[60:63], v[130:133], v[196:199], 0
	v_mfma_f32_16x16x32_bf16 v[56:59], v[148:151], v[196:199], 0
	v_mfma_f32_16x16x32_bf16 v[44:47], v[130:133], v[204:207], 0
	v_mfma_f32_16x16x32_bf16 v[40:43], v[148:151], v[204:207], 0
	v_mfma_f32_16x16x32_bf16 v[28:31], v[130:133], v[212:215], 0
	v_mfma_f32_16x16x32_bf16 v[24:27], v[148:151], v[212:215], 0
	v_mfma_f32_16x16x32_bf16 v[12:15], v[130:133], v[220:223], 0
	v_mfma_f32_16x16x32_bf16 v[8:11], v[148:151], v[220:223], 0
	v_mfma_f32_16x16x32_bf16 v[60:63], v[134:137], v[200:203], v[60:63]
	v_mfma_f32_16x16x32_bf16 v[56:59], v[152:155], v[200:203], v[56:59]
	v_mfma_f32_16x16x32_bf16 v[44:47], v[134:137], v[208:211], v[44:47]
	v_mfma_f32_16x16x32_bf16 v[40:43], v[152:155], v[208:211], v[40:43]
	v_mfma_f32_16x16x32_bf16 v[28:31], v[134:137], v[216:219], v[28:31]
	v_mfma_f32_16x16x32_bf16 v[24:27], v[152:155], v[216:219], v[24:27]
	v_mfma_f32_16x16x32_bf16 v[12:15], v[134:137], v[242:245], v[12:15]
	v_mfma_f32_16x16x32_bf16 v[8:11], v[152:155], v[242:245], v[8:11]
	v_mfma_f32_16x16x32_bf16 v[52:55], v[180:183], v[196:199], 0
	v_mfma_f32_16x16x32_bf16 v[48:51], v[188:191], v[196:199], 0
	v_mfma_f32_16x16x32_bf16 v[36:39], v[180:183], v[204:207], 0
	v_mfma_f32_16x16x32_bf16 v[32:35], v[188:191], v[204:207], 0
	v_mfma_f32_16x16x32_bf16 v[20:23], v[180:183], v[212:215], 0
	v_mfma_f32_16x16x32_bf16 v[16:19], v[188:191], v[212:215], 0
	v_mfma_f32_16x16x32_bf16 v[4:7], v[180:183], v[220:223], 0
	v_mfma_f32_16x16x32_bf16 v[0:3], v[188:191], v[220:223], 0
	v_mfma_f32_16x16x32_bf16 v[52:55], v[184:187], v[200:203], v[52:55]
	v_mfma_f32_16x16x32_bf16 v[48:51], v[192:195], v[200:203], v[48:51]
	v_mfma_f32_16x16x32_bf16 v[36:39], v[184:187], v[208:211], v[36:39]
	v_mfma_f32_16x16x32_bf16 v[32:35], v[192:195], v[208:211], v[32:35]
	v_mfma_f32_16x16x32_bf16 v[20:23], v[184:187], v[216:219], v[20:23]
	v_mfma_f32_16x16x32_bf16 v[16:19], v[192:195], v[216:219], v[16:19]
	v_mfma_f32_16x16x32_bf16 v[4:7], v[184:187], v[242:245], v[4:7]
	v_mfma_f32_16x16x32_bf16 v[0:3], v[192:195], v[242:245], v[0:3]
	s_setprio 0
	s_barrier
	s_add_i32 s45, 0, 0x18000
	s_add_i32 s48, 0, 0x1c000
	v_add_u32_e32 v152, s45, v159
	v_add_u32_e32 v179, s48, v159
	ds_read_b128 v[130:133], v152
	ds_read_b128 v[134:137], v152 offset:1024
	ds_read_b128 v[148:151], v152 offset:2048
	ds_read_b128 v[152:155], v152 offset:3072
	ds_read_b128 v[180:183], v179
	ds_read_b128 v[184:187], v179 offset:1024
	ds_read_b128 v[188:191], v179 offset:2048
	ds_read_b128 v[192:195], v179 offset:3072
	s_add_u32 s22, s28, 0xb0000
	s_addc_u32 s23, s29, 0
	s_mov_b32 m0, s66
	ds_read_b128 v[196:199], v178 offset:32768
	ds_read_b128 v[200:203], v178 offset:33792
	ds_read_b128 v[204:207], v178 offset:34816
	ds_read_b128 v[208:211], v178 offset:35840
	ds_read_b128 v[212:215], v178 offset:36864
	ds_read_b128 v[216:219], v178 offset:37888
	ds_read_b128 v[220:223], v178 offset:38912
	ds_read_b128 v[242:245], v178 offset:39936
	global_load_lds_dwordx4 v138, s[22:23]
	s_mov_b32 m0, s67
	s_nop 0
	global_load_lds_dwordx4 v140, s[22:23]
	s_waitcnt vmcnt(8)
	s_waitcnt lgkmcnt(0)
	s_barrier
	s_setprio 1
	s_waitcnt lgkmcnt(0)
	v_mfma_f32_16x16x32_bf16 v[126:129], v[130:133], v[196:199], v[126:129]
	v_mfma_f32_16x16x32_bf16 v[122:125], v[148:151], v[196:199], v[122:125]
	v_mfma_f32_16x16x32_bf16 v[110:113], v[130:133], v[204:207], v[110:113]
	v_mfma_f32_16x16x32_bf16 v[106:109], v[148:151], v[204:207], v[106:109]
	v_mfma_f32_16x16x32_bf16 v[94:97], v[130:133], v[212:215], v[94:97]
	v_mfma_f32_16x16x32_bf16 v[90:93], v[148:151], v[212:215], v[90:93]
	v_mfma_f32_16x16x32_bf16 v[78:81], v[130:133], v[220:223], v[78:81]
	v_mfma_f32_16x16x32_bf16 v[74:77], v[148:151], v[220:223], v[74:77]
	v_mfma_f32_16x16x32_bf16 v[126:129], v[134:137], v[200:203], v[126:129]
	v_mfma_f32_16x16x32_bf16 v[122:125], v[152:155], v[200:203], v[122:125]
	v_mfma_f32_16x16x32_bf16 v[110:113], v[134:137], v[208:211], v[110:113]
	v_mfma_f32_16x16x32_bf16 v[106:109], v[152:155], v[208:211], v[106:109]
	v_mfma_f32_16x16x32_bf16 v[94:97], v[134:137], v[216:219], v[94:97]
	v_mfma_f32_16x16x32_bf16 v[90:93], v[152:155], v[216:219], v[90:93]
	v_mfma_f32_16x16x32_bf16 v[78:81], v[134:137], v[242:245], v[78:81]
	v_mfma_f32_16x16x32_bf16 v[74:77], v[152:155], v[242:245], v[74:77]
	v_mfma_f32_16x16x32_bf16 v[118:121], v[180:183], v[196:199], v[118:121]
	v_mfma_f32_16x16x32_bf16 v[114:117], v[188:191], v[196:199], v[114:117]
	v_mfma_f32_16x16x32_bf16 v[102:105], v[180:183], v[204:207], v[102:105]
	v_mfma_f32_16x16x32_bf16 v[98:101], v[188:191], v[204:207], v[98:101]
	v_mfma_f32_16x16x32_bf16 v[86:89], v[180:183], v[212:215], v[86:89]
	v_mfma_f32_16x16x32_bf16 v[82:85], v[188:191], v[212:215], v[82:85]
	v_mfma_f32_16x16x32_bf16 v[70:73], v[180:183], v[220:223], v[70:73]
	v_mfma_f32_16x16x32_bf16 v[66:69], v[188:191], v[220:223], v[66:69]
	v_mfma_f32_16x16x32_bf16 v[118:121], v[184:187], v[200:203], v[118:121]
	v_mfma_f32_16x16x32_bf16 v[114:117], v[192:195], v[200:203], v[114:117]
	v_mfma_f32_16x16x32_bf16 v[102:105], v[184:187], v[208:211], v[102:105]
	v_mfma_f32_16x16x32_bf16 v[98:101], v[192:195], v[208:211], v[98:101]
	v_mfma_f32_16x16x32_bf16 v[86:89], v[184:187], v[216:219], v[86:89]
	v_mfma_f32_16x16x32_bf16 v[82:85], v[192:195], v[216:219], v[82:85]
	v_mfma_f32_16x16x32_bf16 v[70:73], v[184:187], v[242:245], v[70:73]
	v_mfma_f32_16x16x32_bf16 v[66:69], v[192:195], v[242:245], v[66:69]
	s_setprio 0
	s_barrier
; #define PG8_STAGE(bufoff, gbase, voff) do { _Pragma("unroll") for (int _i = 0; _i < 2; ++_i) \
;         __builtin_amdgcn_global_load_lds((const unsigned*)((const char*)(gbase) + (voff)[_i]), (PG8_LAS unsigned*)(lds + (bufoff) + ldsw + _i * 8192), 16, 0, 0); } while (0)
; #define PG8_LDA(dst, b, h) do { _Pragma("unroll") for (int m = 0; m < 4; ++m) _Pragma("unroll") for (int k = 0; k < 2; ++k) dst[m][k] = *(const PG8_LAS bf16x8*)(lds + PG8_SA(b, h) + aoff + m * 2048 + k * 1024); } while (0)
; #define PG8_LDB(dst, b, h) do { _Pragma("unroll") for (int n = 0; n < 2; ++n) _Pragma("unroll") for (int k = 0; k < 2; ++k) dst[n][k] = *(const PG8_LAS bf16x8*)(lds + PG8_SB(b, h) + boff + n * 2048 + k * 1024); } while (0)
; #define PG8_MMA(ai, bj, At, Bt) do { __builtin_amdgcn_s_setprio(1); _Pragma("unroll") for (int m = 0; m < 4; ++m) _Pragma("unroll") for (int n = 0; n < 2; ++n) _Pragma("unroll") for (int k = 0; k < 2; ++k) \
;         acc[ai][bj][m][n] = __builtin_amdgcn_mfma_f32_16x16x32_bf16(Bt[n][k], At[m][k], acc[ai][bj][m][n], 0, 0, 0); __builtin_amdgcn_s_setprio(0); } while (0)
; #define PG8_WAIT_V(n) asm volatile("s_waitcnt vmcnt(" #n ")" ::: "memory")
; #define PG8_WAIT_L(n) asm volatile("s_waitcnt lgkmcnt(" #n ")" ::: "memory")
; #define PG8_BAR __builtin_amdgcn_s_barrier()
; #define PG8_SCHED __builtin_amdgcn_sched_barrier(0)
; template <class Epi, class Sched, bool ALIGN_EPI = false, bool SP2 = false>
; __device__ __forceinline__ void gemm_phase(PG8_LAS unsigned char* lds, const Gemm g, const Sched& S, const Epi& E, int tid_in) {
;     ...
;             PG8_LDB(B0, 1, 0); PG8_LDB(B1, 1, 1); PG8_SCHED; PG8_LDA(At, 1, 0); PG8_STAGE(PG8_SA(0, 1), a2 + hstep, voffA);
;             PG8_WAIT_V(8); PG8_WAIT_L(0); PG8_BAR; PG8_MMA(0, 0, At, B0); PG8_MMA(0, 1, At, B1); PG8_BAR; PG8_SCHED;
;             PG8_LDA(At, 1, 1); PG8_STAGE(PG8_SB(1, 0), b3, voffB); PG8_STAGE(PG8_SB(1, 1), b3 + hstep, voffB); PG8_STAGE(PG8_SA(1, 0), a3, voffA);
;             PG8_WAIT_V(8); PG8_WAIT_L(0); PG8_BAR; PG8_MMA(1, 0, At, B0); PG8_MMA(1, 1, At, B1); PG8_BAR; PG8_SCHED;
	s_add_i32 s22, s45, s37
	s_mov_b32 m0, s22
	ds_read_b128 v[196:199], v178 offset:49152
	ds_read_b128 v[200:203], v178 offset:50176
	ds_read_b128 v[204:207], v178 offset:51200
	ds_read_b128 v[208:211], v178 offset:52224
	ds_read_b128 v[212:215], v178 offset:53248
	ds_read_b128 v[216:219], v178 offset:54272
	ds_read_b128 v[220:223], v178 offset:55296
	ds_read_b128 v[242:245], v178 offset:56320
	s_add_u32 s98, s26, 0x80
	s_addc_u32 s99, s27, 0
	global_load_lds_dwordx4 v64, s[98:99]
	s_add_i32 m0, s22, 0x2000
	s_add_u32 s22, s26, 0xb0080
	v_lshl_add_u64 v[156:157], v[172:173], 0, s[92:93]
	s_addc_u32 s23, s27, 0
	s_add_i32 s26, s48, s37
	global_load_lds_dwordx4 v[156:157], off
	s_mov_b32 m0, s26
	s_nop 0
	global_load_lds_dwordx4 v64, s[22:23]
	s_add_i32 m0, s26, 0x2000
	s_nop 0
	global_load_lds_dwordx4 v142, s[22:23]
	s_mov_b32 m0, s69
	s_nop 0
	s_add_u32 s98, s28, 0x80
	s_addc_u32 s99, s29, 0
	global_load_lds_dwordx4 v138, s[98:99]
	s_mov_b32 m0, s74
	s_nop 0
	s_add_u32 s98, s28, 0x80
	s_addc_u32 s99, s29, 0
	global_load_lds_dwordx4 v140, s[98:99]
	s_waitcnt vmcnt(8)
	s_waitcnt lgkmcnt(0)
	s_barrier
	s_setprio 1
	s_waitcnt lgkmcnt(0)
	v_mfma_f32_16x16x32_bf16 v[60:63], v[130:133], v[196:199], v[60:63]
	v_mfma_f32_16x16x32_bf16 v[56:59], v[148:151], v[196:199], v[56:59]
	v_mfma_f32_16x16x32_bf16 v[44:47], v[130:133], v[204:207], v[44:47]
	v_mfma_f32_16x16x32_bf16 v[40:43], v[148:151], v[204:207], v[40:43]
	v_mfma_f32_16x16x32_bf16 v[28:31], v[130:133], v[212:215], v[28:31]
	v_mfma_f32_16x16x32_bf16 v[24:27], v[148:151], v[212:215], v[24:27]
	v_mfma_f32_16x16x32_bf16 v[12:15], v[130:133], v[220:223], v[12:15]
	v_mfma_f32_16x16x32_bf16 v[8:11], v[148:151], v[220:223], v[8:11]
	v_mfma_f32_16x16x32_bf16 v[60:63], v[134:137], v[200:203], v[60:63]
	v_mfma_f32_16x16x32_bf16 v[56:59], v[152:155], v[200:203], v[56:59]
	v_mfma_f32_16x16x32_bf16 v[44:47], v[134:137], v[208:211], v[44:47]
	v_mfma_f32_16x16x32_bf16 v[40:43], v[152:155], v[208:211], v[40:43]
	v_mfma_f32_16x16x32_bf16 v[28:31], v[134:137], v[216:219], v[28:31]
	v_mfma_f32_16x16x32_bf16 v[24:27], v[152:155], v[216:219], v[24:27]
	v_mfma_f32_16x16x32_bf16 v[12:15], v[134:137], v[242:245], v[12:15]
	v_mfma_f32_16x16x32_bf16 v[8:11], v[152:155], v[242:245], v[8:11]
	v_mfma_f32_16x16x32_bf16 v[52:55], v[180:183], v[196:199], v[52:55]
	v_mfma_f32_16x16x32_bf16 v[48:51], v[188:191], v[196:199], v[48:51]
	v_mfma_f32_16x16x32_bf16 v[36:39], v[180:183], v[204:207], v[36:39]
	v_mfma_f32_16x16x32_bf16 v[32:35], v[188:191], v[204:207], v[32:35]
	v_mfma_f32_16x16x32_bf16 v[20:23], v[180:183], v[212:215], v[20:23]
	v_mfma_f32_16x16x32_bf16 v[16:19], v[188:191], v[212:215], v[16:19]
	v_mfma_f32_16x16x32_bf16 v[4:7], v[180:183], v[220:223], v[4:7]
	v_mfma_f32_16x16x32_bf16 v[0:3], v[188:191], v[220:223], v[0:3]
	v_mfma_f32_16x16x32_bf16 v[52:55], v[184:187], v[200:203], v[52:55]
	v_mfma_f32_16x16x32_bf16 v[48:51], v[192:195], v[200:203], v[48:51]
	v_mfma_f32_16x16x32_bf16 v[36:39], v[184:187], v[208:211], v[36:39]
	v_mfma_f32_16x16x32_bf16 v[32:35], v[192:195], v[208:211], v[32:35]
	v_mfma_f32_16x16x32_bf16 v[20:23], v[184:187], v[216:219], v[20:23]
	v_mfma_f32_16x16x32_bf16 v[16:19], v[192:195], v[216:219], v[16:19]
	v_mfma_f32_16x16x32_bf16 v[4:7], v[184:187], v[242:245], v[4:7]
	v_mfma_f32_16x16x32_bf16 v[0:3], v[192:195], v[242:245], v[0:3]
	s_setprio 0
	s_barrier
	s_add_i32 s44, s44, 2
	s_add_u32 s30, s30, 0x100
	s_addc_u32 s31, s31, 0
	s_cmp_gt_u32 s44, 41
	s_mov_b64 s[22:23], s[24:25]
	s_cbranch_scc0 .LBB0_75
	s_branch .Lpeel_exit_2
	.p2align	6

; #define PG8_STAGE(bufoff, gbase, voff) do { _Pragma("unroll") for (int _i = 0; _i < 2; ++_i) \
;         __builtin_amdgcn_global_load_lds((const unsigned*)((const char*)(gbase) + (voff)[_i]), (PG8_LAS unsigned*)(lds + (bufoff) + ldsw + _i * 8192), 16, 0, 0); } while (0)
; #define PG8_LDA(dst, b, h) do { _Pragma("unroll") for (int m = 0; m < 4; ++m) _Pragma("unroll") for (int k = 0; k < 2; ++k) dst[m][k] = *(const PG8_LAS bf16x8*)(lds + PG8_SA(b, h) + aoff + m * 2048 + k * 1024); } while (0)
; #define PG8_LDB(dst, b, h) do { _Pragma("unroll") for (int n = 0; n < 2; ++n) _Pragma("unroll") for (int k = 0; k < 2; ++k) dst[n][k] = *(const PG8_LAS bf16x8*)(lds + PG8_SB(b, h) + boff + n * 2048 + k * 1024); } while (0)
; #define PG8_MMA(ai, bj, At, Bt) do { __builtin_amdgcn_s_setprio(1); _Pragma("unroll") for (int m = 0; m < 4; ++m) _Pragma("unroll") for (int n = 0; n < 2; ++n) _Pragma("unroll") for (int k = 0; k < 2; ++k) \
;         acc[ai][bj][m][n] = __builtin_amdgcn_mfma_f32_16x16x32_bf16(Bt[n][k], At[m][k], acc[ai][bj][m][n], 0, 0, 0); __builtin_amdgcn_s_setprio(0); } while (0)
; template <class Epi, class Sched, bool ALIGN_EPI = false, bool SP2 = false>
; __device__ __forceinline__ void gemm_phase(PG8_LAS unsigned char* lds, const Gemm g, const Sched& S, const Epi& E, int tid_in) {
;     ...
;             if constexpr (SP2) {
;             PG8_LDB(B0, 0, 0); PG8_LDB(B1, 0, 1); PG8_SCHED; PG8_LDA(At, 0, 0); PG8_STAGE(PG8_SA(1, 1), a1 + hstep, voffA);
;             PG8_WAIT_V(8); PG8_WAIT_L(0); PG8_BAR; PG8_MMA(0, 0, At, B0); PG8_MMA(0, 1, At, B1); PG8_BAR; PG8_SCHED;
;             PG8_LDA(At, 0, 1); PG8_STAGE(PG8_SB(0, 0), b2, voffB); PG8_STAGE(PG8_SB(0, 1), b2 + hstep, voffB); PG8_STAGE(PG8_SA(0, 0), a2, voffA);
;             PG8_WAIT_V(8); PG8_WAIT_L(0); PG8_BAR; PG8_MMA(1, 0, At, B0); PG8_MMA(1, 1, At, B1); PG8_BAR; PG8_SCHED;
;             PG8_LDB(B0, 1, 0); PG8_LDB(B1, 1, 1); PG8_SCHED; PG8_LDA(At, 1, 0); PG8_STAGE(PG8_SA(0, 1), a2 + hstep, voffA);
;             PG8_WAIT_V(8); PG8_WAIT_L(0); PG8_BAR; PG8_MMA(0, 0, At, B0); PG8_MMA(0, 1, At, B1); PG8_BAR; PG8_SCHED;
;             PG8_LDA(At, 1, 1); PG8_STAGE(PG8_SB(1, 0), b3, voffB); PG8_STAGE(PG8_SB(1, 1), b3 + hstep, voffB); PG8_STAGE(PG8_SA(1, 0), a3, voffA);
;             PG8_WAIT_V(8); PG8_WAIT_L(0); PG8_BAR; PG8_MMA(1, 0, At, B0); PG8_MMA(1, 1, At, B1); PG8_BAR; PG8_SCHED;
.LBB0_241:
	s_ashr_i32 s51, s50, 31
	s_lshl_b64 s[30:31], s[50:51], 19
	s_add_u32 s56, s37, s30
	s_addc_u32 s57, s62, s31
	s_and_b64 s[30:31], s[40:41], exec
	s_cselect_b32 s23, s57, s27
	s_cselect_b32 s25, s56, s26
	s_ashr_i32 s49, s48, 31
	s_lshl_b64 s[30:31], s[48:49], 19
	s_add_u32 s60, s63, s30
	s_addc_u32 s61, s66, s31
	s_and_b64 s[30:31], s[40:41], exec
	s_cselect_b32 s34, s61, s29
	s_cselect_b32 s35, s60, s28
	s_add_u32 s26, s26, 0x40080
	s_addc_u32 s27, s27, 0
	s_add_u32 s42, s28, 0x100
	s_addc_u32 s43, s29, 0
	s_mov_b32 s44, -2
	s_add_u32 s28, s26, 0xfffc0080
	s_addc_u32 s29, s27, -1
	s_add_i32 s45, 0, 0x10000
	s_cmp_eq_u32 s44, 12
	s_cselect_b32 s31, s23, s29
	s_cselect_b32 s30, s25, s28
	v_add_u32_e32 v64, s45, v171
	s_cselect_b32 s29, s34, s43
	s_cselect_b32 s28, s35, s42
	s_add_i32 s49, 0, 0x14000
	ds_read_b128 v[122:125], v64
	ds_read_b128 v[126:129], v64 offset:1024
	ds_read_b128 v[130:133], v64 offset:2048
	ds_read_b128 v[134:137], v64 offset:3072
	v_add_u32_e32 v64, s49, v171
	ds_read_b128 v[146:149], v64
	ds_read_b128 v[150:153], v64 offset:1024
	ds_read_b128 v[154:157], v64 offset:2048
	ds_read_b128 v[158:161], v64 offset:3072
	s_add_i32 m0, s67, 0xc000
	ds_read_b128 v[162:165], v216
	ds_read_b128 v[166:169], v216 offset:1024
	ds_read_b128 v[192:195], v216 offset:2048
	ds_read_b128 v[196:199], v216 offset:3072
	ds_read_b128 v[200:203], v216 offset:4096
	ds_read_b128 v[204:207], v216 offset:5120
	ds_read_b128 v[208:211], v216 offset:6144
	ds_read_b128 v[212:215], v216 offset:7168
	global_load_lds_dwordx4 v188, s[26:27]
	s_add_i32 m0, s67, 0xe000
	s_nop 0
	global_load_lds_dwordx4 v190, s[26:27]
	s_waitcnt vmcnt(8)
	s_waitcnt lgkmcnt(0)
	s_barrier
	s_setprio 1
	s_waitcnt lgkmcnt(0)
	v_mfma_f32_16x16x32_bf16 v[114:117], v[122:125], v[162:165], 0
	v_mfma_f32_16x16x32_bf16 v[106:109], v[130:133], v[162:165], 0
	v_mfma_f32_16x16x32_bf16 v[142:145], v[122:125], v[192:195], 0
	v_mfma_f32_16x16x32_bf16 v[44:47], v[130:133], v[192:195], 0
	v_mfma_f32_16x16x32_bf16 v[110:113], v[122:125], v[200:203], 0
	v_mfma_f32_16x16x32_bf16 v[36:39], v[130:133], v[200:203], 0
	v_mfma_f32_16x16x32_bf16 v[118:121], v[122:125], v[208:211], 0
	v_mfma_f32_16x16x32_bf16 v[52:55], v[130:133], v[208:211], 0
	v_mfma_f32_16x16x32_bf16 v[114:117], v[126:129], v[166:169], v[114:117]
	v_mfma_f32_16x16x32_bf16 v[106:109], v[134:137], v[166:169], v[106:109]
	v_mfma_f32_16x16x32_bf16 v[142:145], v[126:129], v[196:199], v[142:145]
	v_mfma_f32_16x16x32_bf16 v[44:47], v[134:137], v[196:199], v[44:47]
	v_mfma_f32_16x16x32_bf16 v[110:113], v[126:129], v[204:207], v[110:113]
	v_mfma_f32_16x16x32_bf16 v[36:39], v[134:137], v[204:207], v[36:39]
	v_mfma_f32_16x16x32_bf16 v[118:121], v[126:129], v[212:215], v[118:121]
	v_mfma_f32_16x16x32_bf16 v[52:55], v[134:137], v[212:215], v[52:55]
	v_mfma_f32_16x16x32_bf16 v[102:105], v[146:149], v[162:165], 0
	v_mfma_f32_16x16x32_bf16 v[78:81], v[154:157], v[162:165], 0
	v_mfma_f32_16x16x32_bf16 v[138:141], v[146:149], v[192:195], 0
	v_mfma_f32_16x16x32_bf16 v[40:43], v[154:157], v[192:195], 0
	v_mfma_f32_16x16x32_bf16 v[98:101], v[146:149], v[200:203], 0
	v_mfma_f32_16x16x32_bf16 v[32:35], v[154:157], v[200:203], 0
	v_mfma_f32_16x16x32_bf16 v[94:97], v[146:149], v[208:211], 0
	v_mfma_f32_16x16x32_bf16 v[48:51], v[154:157], v[208:211], 0
	v_mfma_f32_16x16x32_bf16 v[102:105], v[150:153], v[166:169], v[102:105]
	v_mfma_f32_16x16x32_bf16 v[78:81], v[158:161], v[166:169], v[78:81]
	v_mfma_f32_16x16x32_bf16 v[138:141], v[150:153], v[196:199], v[138:141]
	v_mfma_f32_16x16x32_bf16 v[40:43], v[158:161], v[196:199], v[40:43]
	v_mfma_f32_16x16x32_bf16 v[98:101], v[150:153], v[204:207], v[98:101]
	v_mfma_f32_16x16x32_bf16 v[32:35], v[158:161], v[204:207], v[32:35]
	v_mfma_f32_16x16x32_bf16 v[94:97], v[150:153], v[212:215], v[94:97]
	v_mfma_f32_16x16x32_bf16 v[48:51], v[158:161], v[212:215], v[48:51]
	s_setprio 0
	s_barrier
	s_add_i32 s45, s45, s9
	v_lshl_add_u64 v[172:173], s[28:29], 0, v[178:179]
	s_mov_b32 m0, s45
	ds_read_b128 v[162:165], v216 offset:16384
	ds_read_b128 v[166:169], v216 offset:17408
	ds_read_b128 v[192:195], v216 offset:18432
	ds_read_b128 v[196:199], v216 offset:19456
	ds_read_b128 v[200:203], v216 offset:20480
	ds_read_b128 v[204:207], v216 offset:21504
	ds_read_b128 v[208:211], v216 offset:22528
	ds_read_b128 v[212:215], v216 offset:23552
	global_load_lds_dwordx4 v178, s[28:29]
	s_add_i32 m0, s45, 0x2000
	s_add_u32 s46, s28, 0x40000
	v_lshl_add_u64 v[220:221], s[28:29], 0, v[182:183]
	s_addc_u32 s47, s29, 0
	s_add_i32 s45, s49, s9
	global_load_lds_dwordx4 v182, s[28:29]
	s_mov_b32 m0, s45
	v_lshl_add_u64 v[224:225], s[30:31], 0, v[180:181]
	global_load_lds_dwordx4 v178, s[46:47]
	s_add_i32 m0, s45, 0x2000
	s_nop 0
	global_load_lds_dwordx4 v182, s[46:47]
	v_lshl_add_u64 v[222:223], s[30:31], 0, v[176:177]
	s_mov_b32 m0, s67
	s_nop 0
	global_load_lds_dwordx4 v176, s[30:31]
	s_mov_b32 m0, s69
	s_nop 0
	global_load_lds_dwordx4 v180, s[30:31]
	s_waitcnt vmcnt(8)
	s_waitcnt lgkmcnt(0)
	s_barrier
; #define PG8_STAGE(bufoff, gbase, voff) do { _Pragma("unroll") for (int _i = 0; _i < 2; ++_i) \
;         __builtin_amdgcn_global_load_lds((const unsigned*)((const char*)(gbase) + (voff)[_i]), (PG8_LAS unsigned*)(lds + (bufoff) + ldsw + _i * 8192), 16, 0, 0); } while (0)
; #define PG8_LDA(dst, b, h) do { _Pragma("unroll") for (int m = 0; m < 4; ++m) _Pragma("unroll") for (int k = 0; k < 2; ++k) dst[m][k] = *(const PG8_LAS bf16x8*)(lds + PG8_SA(b, h) + aoff + m * 2048 + k * 1024); } while (0)
; #define PG8_LDB(dst, b, h) do { _Pragma("unroll") for (int n = 0; n < 2; ++n) _Pragma("unroll") for (int k = 0; k < 2; ++k) dst[n][k] = *(const PG8_LAS bf16x8*)(lds + PG8_SB(b, h) + boff + n * 2048 + k * 1024); } while (0)
; #define PG8_MMA(ai, bj, At, Bt) do { __builtin_amdgcn_s_setprio(1); _Pragma("unroll") for (int m = 0; m < 4; ++m) _Pragma("unroll") for (int n = 0; n < 2; ++n) _Pragma("unroll") for (int k = 0; k < 2; ++k) \
;         acc[ai][bj][m][n] = __builtin_amdgcn_mfma_f32_16x16x32_bf16(Bt[n][k], At[m][k], acc[ai][bj][m][n], 0, 0, 0); __builtin_amdgcn_s_setprio(0); } while (0)
; #define PG8_WAIT_V(n) asm volatile("s_waitcnt vmcnt(" #n ")" ::: "memory")
; #define PG8_WAIT_L(n) asm volatile("s_waitcnt lgkmcnt(" #n ")" ::: "memory")
; #define PG8_BAR __builtin_amdgcn_s_barrier()
; #define PG8_SCHED __builtin_amdgcn_sched_barrier(0)
; template <class Epi, class Sched, bool ALIGN_EPI = false, bool SP2 = false>
; __device__ __forceinline__ void gemm_phase(PG8_LAS unsigned char* lds, const Gemm g, const Sched& S, const Epi& E, int tid_in) {
;     ...
;             PG8_WAIT_V(8); PG8_WAIT_L(0); PG8_BAR; PG8_MMA(0, 0, At, B0); PG8_MMA(0, 1, At, B1); PG8_BAR; PG8_SCHED;
;             PG8_LDA(At, 0, 1); PG8_STAGE(PG8_SB(0, 0), b2, voffB); PG8_STAGE(PG8_SB(0, 1), b2 + hstep, voffB); PG8_STAGE(PG8_SA(0, 0), a2, voffA);
;             PG8_WAIT_V(8); PG8_WAIT_L(0); PG8_BAR; PG8_MMA(1, 0, At, B0); PG8_MMA(1, 1, At, B1); PG8_BAR; PG8_SCHED;
;             PG8_LDB(B0, 1, 0); PG8_LDB(B1, 1, 1); PG8_SCHED; PG8_LDA(At, 1, 0); PG8_STAGE(PG8_SA(0, 1), a2 + hstep, voffA);
;             PG8_WAIT_V(8); PG8_WAIT_L(0); PG8_BAR; PG8_MMA(0, 0, At, B0); PG8_MMA(0, 1, At, B1); PG8_BAR; PG8_SCHED;
	s_setprio 1
	s_waitcnt lgkmcnt(0)
	v_mfma_f32_16x16x32_bf16 v[82:85], v[122:125], v[162:165], 0
	v_mfma_f32_16x16x32_bf16 v[20:23], v[130:133], v[162:165], 0
	v_mfma_f32_16x16x32_bf16 v[70:73], v[122:125], v[192:195], 0
	v_mfma_f32_16x16x32_bf16 v[12:15], v[130:133], v[192:195], 0
	v_mfma_f32_16x16x32_bf16 v[60:63], v[122:125], v[200:203], 0
	v_mfma_f32_16x16x32_bf16 v[4:7], v[130:133], v[200:203], 0
	v_mfma_f32_16x16x32_bf16 v[90:93], v[122:125], v[208:211], 0
	v_mfma_f32_16x16x32_bf16 v[28:31], v[130:133], v[208:211], 0
	v_mfma_f32_16x16x32_bf16 v[82:85], v[126:129], v[166:169], v[82:85]
	v_mfma_f32_16x16x32_bf16 v[20:23], v[134:137], v[166:169], v[20:23]
	v_mfma_f32_16x16x32_bf16 v[70:73], v[126:129], v[196:199], v[70:73]
	v_mfma_f32_16x16x32_bf16 v[12:15], v[134:137], v[196:199], v[12:15]
	v_mfma_f32_16x16x32_bf16 v[60:63], v[126:129], v[204:207], v[60:63]
	v_mfma_f32_16x16x32_bf16 v[4:7], v[134:137], v[204:207], v[4:7]
	v_mfma_f32_16x16x32_bf16 v[90:93], v[126:129], v[212:215], v[90:93]
	v_mfma_f32_16x16x32_bf16 v[28:31], v[134:137], v[212:215], v[28:31]
	v_mfma_f32_16x16x32_bf16 v[74:77], v[146:149], v[162:165], 0
	v_mfma_f32_16x16x32_bf16 v[16:19], v[154:157], v[162:165], 0
	v_mfma_f32_16x16x32_bf16 v[66:69], v[146:149], v[192:195], 0
	v_mfma_f32_16x16x32_bf16 v[8:11], v[154:157], v[192:195], 0
	v_mfma_f32_16x16x32_bf16 v[56:59], v[146:149], v[200:203], 0
	v_mfma_f32_16x16x32_bf16 v[0:3], v[154:157], v[200:203], 0
	v_mfma_f32_16x16x32_bf16 v[86:89], v[146:149], v[208:211], 0
	v_mfma_f32_16x16x32_bf16 v[24:27], v[154:157], v[208:211], 0
	v_mfma_f32_16x16x32_bf16 v[74:77], v[150:153], v[166:169], v[74:77]
	v_mfma_f32_16x16x32_bf16 v[16:19], v[158:161], v[166:169], v[16:19]
	v_mfma_f32_16x16x32_bf16 v[66:69], v[150:153], v[196:199], v[66:69]
	v_mfma_f32_16x16x32_bf16 v[8:11], v[158:161], v[196:199], v[8:11]
	v_mfma_f32_16x16x32_bf16 v[56:59], v[150:153], v[204:207], v[56:59]
	v_mfma_f32_16x16x32_bf16 v[0:3], v[158:161], v[204:207], v[0:3]
	v_mfma_f32_16x16x32_bf16 v[86:89], v[150:153], v[212:215], v[86:89]
	v_mfma_f32_16x16x32_bf16 v[24:27], v[158:161], v[212:215], v[24:27]
	s_setprio 0
	s_barrier
	s_add_i32 s45, 0, 0x18000
	v_add_u32_e32 v64, s45, v171
	s_add_i32 s46, 0, 0x1c000
	ds_read_b128 v[122:125], v64
	ds_read_b128 v[126:129], v64 offset:1024
	ds_read_b128 v[130:133], v64 offset:2048
	ds_read_b128 v[134:137], v64 offset:3072
	v_add_u32_e32 v64, s46, v171
	ds_read_b128 v[146:149], v64
	ds_read_b128 v[150:153], v64 offset:1024
	ds_read_b128 v[154:157], v64 offset:2048
	ds_read_b128 v[158:161], v64 offset:3072
	s_add_u32 s30, s30, 0x40000
	s_addc_u32 s31, s31, 0
	s_mov_b32 m0, s79
	ds_read_b128 v[162:165], v216 offset:32768
	ds_read_b128 v[166:169], v216 offset:33792
	ds_read_b128 v[192:195], v216 offset:34816
	ds_read_b128 v[196:199], v216 offset:35840
	ds_read_b128 v[200:203], v216 offset:36864
	ds_read_b128 v[204:207], v216 offset:37888
	ds_read_b128 v[208:211], v216 offset:38912
	ds_read_b128 v[212:215], v216 offset:39936
	global_load_lds_dwordx4 v176, s[30:31]
	s_mov_b32 m0, s82
	s_nop 0
	global_load_lds_dwordx4 v180, s[30:31]
	s_waitcnt vmcnt(8)
	s_waitcnt lgkmcnt(0)
	s_barrier
	s_setprio 1
	s_waitcnt lgkmcnt(0)
	v_mfma_f32_16x16x32_bf16 v[114:117], v[122:125], v[162:165], v[114:117]
	v_mfma_f32_16x16x32_bf16 v[106:109], v[130:133], v[162:165], v[106:109]
	v_mfma_f32_16x16x32_bf16 v[142:145], v[122:125], v[192:195], v[142:145]
	v_mfma_f32_16x16x32_bf16 v[44:47], v[130:133], v[192:195], v[44:47]
	v_mfma_f32_16x16x32_bf16 v[110:113], v[122:125], v[200:203], v[110:113]
	v_mfma_f32_16x16x32_bf16 v[36:39], v[130:133], v[200:203], v[36:39]
	v_mfma_f32_16x16x32_bf16 v[118:121], v[122:125], v[208:211], v[118:121]
	v_mfma_f32_16x16x32_bf16 v[52:55], v[130:133], v[208:211], v[52:55]
	v_mfma_f32_16x16x32_bf16 v[114:117], v[126:129], v[166:169], v[114:117]
	v_mfma_f32_16x16x32_bf16 v[106:109], v[134:137], v[166:169], v[106:109]
	v_mfma_f32_16x16x32_bf16 v[142:145], v[126:129], v[196:199], v[142:145]
	v_mfma_f32_16x16x32_bf16 v[44:47], v[134:137], v[196:199], v[44:47]
	v_mfma_f32_16x16x32_bf16 v[110:113], v[126:129], v[204:207], v[110:113]
	v_mfma_f32_16x16x32_bf16 v[36:39], v[134:137], v[204:207], v[36:39]
	v_mfma_f32_16x16x32_bf16 v[118:121], v[126:129], v[212:215], v[118:121]
	v_mfma_f32_16x16x32_bf16 v[52:55], v[134:137], v[212:215], v[52:55]
	v_mfma_f32_16x16x32_bf16 v[102:105], v[146:149], v[162:165], v[102:105]
	v_mfma_f32_16x16x32_bf16 v[78:81], v[154:157], v[162:165], v[78:81]
	v_mfma_f32_16x16x32_bf16 v[138:141], v[146:149], v[192:195], v[138:141]
	v_mfma_f32_16x16x32_bf16 v[40:43], v[154:157], v[192:195], v[40:43]
	v_mfma_f32_16x16x32_bf16 v[98:101], v[146:149], v[200:203], v[98:101]
	v_mfma_f32_16x16x32_bf16 v[32:35], v[154:157], v[200:203], v[32:35]
	v_mfma_f32_16x16x32_bf16 v[94:97], v[146:149], v[208:211], v[94:97]
	v_mfma_f32_16x16x32_bf16 v[48:51], v[154:157], v[208:211], v[48:51]
	v_mfma_f32_16x16x32_bf16 v[102:105], v[150:153], v[166:169], v[102:105]
	v_mfma_f32_16x16x32_bf16 v[78:81], v[158:161], v[166:169], v[78:81]
	v_mfma_f32_16x16x32_bf16 v[138:141], v[150:153], v[196:199], v[138:141]
	v_mfma_f32_16x16x32_bf16 v[40:43], v[158:161], v[196:199], v[40:43]
	v_mfma_f32_16x16x32_bf16 v[98:101], v[150:153], v[204:207], v[98:101]
	v_mfma_f32_16x16x32_bf16 v[32:35], v[158:161], v[204:207], v[32:35]
	v_mfma_f32_16x16x32_bf16 v[94:97], v[150:153], v[212:215], v[94:97]
	v_mfma_f32_16x16x32_bf16 v[48:51], v[158:161], v[212:215], v[48:51]
	s_setprio 0
	s_barrier
; #define PG8_STAGE(bufoff, gbase, voff) do { _Pragma("unroll") for (int _i = 0; _i < 2; ++_i) \
;         __builtin_amdgcn_global_load_lds((const unsigned*)((const char*)(gbase) + (voff)[_i]), (PG8_LAS unsigned*)(lds + (bufoff) + ldsw + _i * 8192), 16, 0, 0); } while (0)
; #define PG8_LDA(dst, b, h) do { _Pragma("unroll") for (int m = 0; m < 4; ++m) _Pragma("unroll") for (int k = 0; k < 2; ++k) dst[m][k] = *(const PG8_LAS bf16x8*)(lds + PG8_SA(b, h) + aoff + m * 2048 + k * 1024); } while (0)
; #define PG8_MMA(ai, bj, At, Bt) do { __builtin_amdgcn_s_setprio(1); _Pragma("unroll") for (int m = 0; m < 4; ++m) _Pragma("unroll") for (int n = 0; n < 2; ++n) _Pragma("unroll") for (int k = 0; k < 2; ++k) \
;         acc[ai][bj][m][n] = __builtin_amdgcn_mfma_f32_16x16x32_bf16(Bt[n][k], At[m][k], acc[ai][bj][m][n], 0, 0, 0); __builtin_amdgcn_s_setprio(0); } while (0)
; #define PG8_WAIT_V(n) asm volatile("s_waitcnt vmcnt(" #n ")" ::: "memory")
; #define PG8_WAIT_L(n) asm volatile("s_waitcnt lgkmcnt(" #n ")" ::: "memory")
; #define PG8_BAR __builtin_amdgcn_s_barrier()
; #define PG8_SCHED __builtin_amdgcn_sched_barrier(0)
; template <class Epi, class Sched, bool ALIGN_EPI = false, bool SP2 = false>
; __device__ __forceinline__ void gemm_phase(PG8_LAS unsigned char* lds, const Gemm g, const Sched& S, const Epi& E, int tid_in) {
;     ...
;             PG8_WAIT_V(8); PG8_WAIT_L(0); PG8_BAR; PG8_MMA(0, 0, At, B0); PG8_MMA(0, 1, At, B1); PG8_BAR; PG8_SCHED;
;             PG8_LDA(At, 1, 1); PG8_STAGE(PG8_SB(1, 0), b3, voffB); PG8_STAGE(PG8_SB(1, 1), b3 + hstep, voffB); PG8_STAGE(PG8_SA(1, 0), a3, voffA);
;             PG8_WAIT_V(8); PG8_WAIT_L(0); PG8_BAR; PG8_MMA(1, 0, At, B0); PG8_MMA(1, 1, At, B1); PG8_BAR; PG8_SCHED;
	s_add_i32 s30, s45, s9
	s_mov_b32 m0, s30
	ds_read_b128 v[162:165], v216 offset:49152
	ds_read_b128 v[166:169], v216 offset:50176
	ds_read_b128 v[192:195], v216 offset:51200
	ds_read_b128 v[196:199], v216 offset:52224
	ds_read_b128 v[200:203], v216 offset:53248
	ds_read_b128 v[204:207], v216 offset:54272
	ds_read_b128 v[208:211], v216 offset:55296
	ds_read_b128 v[212:215], v216 offset:56320
	s_add_u32 s98, s28, 0x80
	s_addc_u32 s99, s29, 0
	global_load_lds_dwordx4 v178, s[98:99]
	s_add_i32 m0, s30, 0x2000
	s_add_u32 s28, s28, 0x40080
	v_lshl_add_u64 v[172:173], v[220:221], 0, s[92:93]
	s_addc_u32 s29, s29, 0
	s_add_i32 s30, s46, s9
	global_load_lds_dwordx4 v[172:173], off
	s_mov_b32 m0, s30
	s_nop 0
	global_load_lds_dwordx4 v178, s[28:29]
	s_add_i32 m0, s30, 0x2000
	s_nop 0
	global_load_lds_dwordx4 v182, s[28:29]
	v_lshl_add_u64 v[172:173], v[222:223], 0, s[92:93]
	s_mov_b32 m0, s85
	s_nop 0
	global_load_lds_dwordx4 v[172:173], off
	v_lshl_add_u64 v[172:173], v[224:225], 0, s[92:93]
	s_mov_b32 m0, s8
	s_nop 0
	global_load_lds_dwordx4 v[172:173], off
	s_waitcnt vmcnt(8)
	s_waitcnt lgkmcnt(0)
	s_barrier
	s_setprio 1
	s_waitcnt lgkmcnt(0)
	v_mfma_f32_16x16x32_bf16 v[82:85], v[122:125], v[162:165], v[82:85]
	v_mfma_f32_16x16x32_bf16 v[20:23], v[130:133], v[162:165], v[20:23]
	v_mfma_f32_16x16x32_bf16 v[70:73], v[122:125], v[192:195], v[70:73]
	v_mfma_f32_16x16x32_bf16 v[12:15], v[130:133], v[192:195], v[12:15]
	v_mfma_f32_16x16x32_bf16 v[60:63], v[122:125], v[200:203], v[60:63]
	v_mfma_f32_16x16x32_bf16 v[4:7], v[130:133], v[200:203], v[4:7]
	v_mfma_f32_16x16x32_bf16 v[90:93], v[122:125], v[208:211], v[90:93]
	v_mfma_f32_16x16x32_bf16 v[28:31], v[130:133], v[208:211], v[28:31]
	v_mfma_f32_16x16x32_bf16 v[82:85], v[126:129], v[166:169], v[82:85]
	v_mfma_f32_16x16x32_bf16 v[20:23], v[134:137], v[166:169], v[20:23]
	v_mfma_f32_16x16x32_bf16 v[70:73], v[126:129], v[196:199], v[70:73]
	v_mfma_f32_16x16x32_bf16 v[12:15], v[134:137], v[196:199], v[12:15]
	v_mfma_f32_16x16x32_bf16 v[60:63], v[126:129], v[204:207], v[60:63]
	v_mfma_f32_16x16x32_bf16 v[4:7], v[134:137], v[204:207], v[4:7]
	v_mfma_f32_16x16x32_bf16 v[90:93], v[126:129], v[212:215], v[90:93]
	v_mfma_f32_16x16x32_bf16 v[28:31], v[134:137], v[212:215], v[28:31]
	v_mfma_f32_16x16x32_bf16 v[74:77], v[146:149], v[162:165], v[74:77]
	v_mfma_f32_16x16x32_bf16 v[16:19], v[154:157], v[162:165], v[16:19]
	v_mfma_f32_16x16x32_bf16 v[66:69], v[146:149], v[192:195], v[66:69]
	v_mfma_f32_16x16x32_bf16 v[8:11], v[154:157], v[192:195], v[8:11]
	v_mfma_f32_16x16x32_bf16 v[56:59], v[146:149], v[200:203], v[56:59]
	v_mfma_f32_16x16x32_bf16 v[0:3], v[154:157], v[200:203], v[0:3]
	v_mfma_f32_16x16x32_bf16 v[86:89], v[146:149], v[208:211], v[86:89]
	v_mfma_f32_16x16x32_bf16 v[24:27], v[154:157], v[208:211], v[24:27]
	v_mfma_f32_16x16x32_bf16 v[74:77], v[150:153], v[166:169], v[74:77]
	v_mfma_f32_16x16x32_bf16 v[16:19], v[158:161], v[166:169], v[16:19]
	v_mfma_f32_16x16x32_bf16 v[66:69], v[150:153], v[196:199], v[66:69]
	v_mfma_f32_16x16x32_bf16 v[8:11], v[158:161], v[196:199], v[8:11]
	v_mfma_f32_16x16x32_bf16 v[56:59], v[150:153], v[204:207], v[56:59]
	v_mfma_f32_16x16x32_bf16 v[0:3], v[158:161], v[204:207], v[0:3]
	v_mfma_f32_16x16x32_bf16 v[86:89], v[150:153], v[212:215], v[86:89]
	v_mfma_f32_16x16x32_bf16 v[24:27], v[158:161], v[212:215], v[24:27]
	s_setprio 0
	s_barrier
	s_add_i32 s44, s44, 2
	s_add_u32 s26, s26, 0x100
	s_addc_u32 s27, s27, 0
	s_add_u32 s42, s42, 0x100
	s_addc_u32 s43, s43, 0
	s_cmp_gt_u32 s44, 13
	s_cbranch_scc0 .LBB0_242
	s_branch .Lpeel_exit_1
	.p2align	6

; template <class Epi, class Sched, bool ALIGN_EPI = false, bool SP2 = false>
; __device__ __forceinline__ void gemm_phase(PG8_LAS unsigned char* lds, const Gemm g, const Sched& S, const Epi& E, int tid_in) {
;     ...
;         for (int seg = 0; seg < (Epi::KSEG ? 3 : 1); ++seg) {
;         if constexpr (Epi::KSEG) { if (seg > 0) E.kscale(acc, seg, cur, wr, fr); }
;         const int tb_ = Epi::KSEG ? (seg == 0 ? 0 : (seg == 1 ? 8 : 12)) : 0, te_ = Epi::KSEG ? (seg == 0 ? 8 : (seg == 1 ? 12 : nt)) : nt;
; #pragma unroll 1
;         for (int t = tb_; t < te_; t += 2) {
.LBB0_367:
	s_cmp_eq_u32 s51, 1
	s_cselect_b32 s34, 8, 12
	s_cselect_b32 s35, 12, 16
	s_and_b64 s[30:31], exec, s[30:31]
	s_cselect_b32 s55, 0, s34
	s_cselect_b32 s57, 8, s35
	s_cmp_ge_u32 s55, s57
	s_cbranch_scc1 .LBB0_364
	s_lshl_b32 s72, s55, 7
	s_mov_b64 s[30:31], 0x700
	v_mov_b64_e32 v[66:67], v[146:147]
	v_mov_b64_e32 v[148:149], v[144:145]
	s_mov_b64 s[44:45], s[28:29]
	s_mov_b64 vcc, s[26:27]
	.p2align	6

.Lmla_nov_p:
	s_cmp_lt_u32 s33, 4
	s_cbranch_scc1 .Lmla_loop
	s_barrier
	.p2align	6

; #define LAS __attribute__((address_space(3)))
; template <int MODE> DI void attn_unit(int b, int qb, const bf16* Qb, int qpitch, const bf16* Kb, int kpitch, const bf16* VT, bf16* O, float* ssq, ...
;     ...
;         if (more) ATT_STORE(buf ^ 1);
;         if (REV) {
;             int vote = 0;
;             if (seen && kt > 0) { const float fb0 = ((const LAS float*)(lds + FOFF + buf * 256))[0]; const float kb = MS[32 + ((kt - 1) >> 1)]; vote = __all((qn * kb + fb0 - m) < -40.0f) ? 1 : 0; }
;             volatile LAS int* vt = (volatile LAS int*)(MS + 64) + (it & 1) * 8;
;             if (lane == 0) vt[wave] = vote;
;             __syncthreads();
;             const int stop = vt[0] & vt[1] & vt[2] & vt[3] & vt[4] & vt[5] & vt[6] & vt[7];
;             if (stop) break;
;         } else {
;             __syncthreads();
;         }
;         buf ^= 1;
;     }
.LBB0_500:
	s_or_b64 exec, exec, s[22:23]
	v_mov_b32_e32 v32, s26
	s_waitcnt lgkmcnt(0)
	s_barrier
	ds_read_b32 v33, v32 offset:36608
	ds_read_b32 v34, v32 offset:36612
	s_movk_i32 s26, 0xff80
	s_mov_b32 s27, -1
	v_lshl_add_u64 v[176:177], v[176:177], 0, s[26:27]
	s_movk_i32 s26, 0xfc00
	s_waitcnt lgkmcnt(0)
	v_and_b32_e32 v33, v34, v33
	ds_read_b32 v34, v32 offset:36616
	s_mov_b32 s27, -1
	v_lshl_add_u64 v[178:179], v[178:179], 0, s[26:27]
	s_mov_b32 s26, 0xfffc0000
	s_mov_b32 s27, -1
	s_waitcnt lgkmcnt(0)
	v_and_b32_e32 v33, v33, v34
	ds_read_b32 v34, v32 offset:36620
	s_xor_b32 s72, s72, 1
	s_add_i32 s61, s61, -1
	s_sub_i32 s59, s59, 64
	v_lshl_add_u64 v[180:181], v[180:181], 0, s[26:27]
	s_waitcnt lgkmcnt(0)
	v_and_b32_e32 v33, v33, v34
	ds_read_b32 v34, v32 offset:36624
	s_add_i32 s75, s75, 1
	s_add_i32 s74, s74, 8
	s_waitcnt lgkmcnt(0)
	v_and_b32_e32 v33, v33, v34
	ds_read_b32 v34, v32 offset:36628
	s_waitcnt lgkmcnt(0)
	v_and_b32_e32 v33, v33, v34
	ds_read_b32 v34, v32 offset:36632
	ds_read_b32 v32, v32 offset:36636
	s_waitcnt lgkmcnt(1)
	v_and_b32_e32 v33, v33, v34
	s_waitcnt lgkmcnt(0)
	v_and_b32_e32 v32, v33, v32
	v_cmp_ne_u32_e64 s[22:23], 0, v32
	s_and_b64 vcc, exec, s[22:23]
	s_cbranch_vccnz .LBB0_521
	.p2align	6

; template <int MODE> DI void attn_unit(int b, int qb, const bf16* Qb, int qpitch, const bf16* Kb, int kpitch, const bf16* VT, bf16* O, float* ssq, ...
;     ...
;         } else {
;             __syncthreads();
;         }
;         buf ^= 1;
;     }
.LBB0_531:
	s_add_i32 s60, s60, 1
	s_add_i32 s18, s18, 64
	s_cmp_eq_u32 s58, s60
	v_add_u32_e32 v153, 0x100, v153
	s_waitcnt lgkmcnt(0)
	s_barrier
	s_cbranch_scc1 .LBB0_541
	.p2align	6

; #define PG8_STAGE(bufoff, gbase, voff) do { _Pragma("unroll") for (int _i = 0; _i < 2; ++_i) \
;         __builtin_amdgcn_global_load_lds((const unsigned*)((const char*)(gbase) + (voff)[_i]), (PG8_LAS unsigned*)(lds + (bufoff) + ldsw + _i * 8192), 16, 0, 0); } while (0)
; #define PG8_LDA(dst, b, h) do { _Pragma("unroll") for (int m = 0; m < 4; ++m) _Pragma("unroll") for (int k = 0; k < 2; ++k) dst[m][k] = *(const PG8_LAS bf16x8*)(lds + PG8_SA(b, h) + aoff + m * 2048 + k * 1024); } while (0)
; #define PG8_LDB(dst, b, h) do { _Pragma("unroll") for (int n = 0; n < 2; ++n) _Pragma("unroll") for (int k = 0; k < 2; ++k) dst[n][k] = *(const PG8_LAS bf16x8*)(lds + PG8_SB(b, h) + boff + n * 2048 + k * 1024); } while (0)
; #define PG8_WAIT_V(n) asm volatile("s_waitcnt vmcnt(" #n ")" ::: "memory")
; #define PG8_WAIT_L(n) asm volatile("s_waitcnt lgkmcnt(" #n ")" ::: "memory")
; template <class Epi, class Sched, bool ALIGN_EPI = false, bool SP2 = false>
; __device__ __forceinline__ void gemm_phase(PG8_LAS unsigned char* lds, const Gemm g, const Sched& S, const Epi& E, int tid_in) {
;     ...
;             if constexpr (SP2) {
;             PG8_LDB(B0, 0, 0); PG8_LDB(B1, 0, 1); PG8_SCHED; PG8_LDA(At, 0, 0); PG8_STAGE(PG8_SA(1, 1), a1 + hstep, voffA);
;             PG8_WAIT_V(8); PG8_WAIT_L(0); PG8_BAR; PG8_MMA(0, 0, At, B0); PG8_MMA(0, 1, At, B1); PG8_BAR; PG8_SCHED;
;             PG8_LDA(At, 0, 1); PG8_STAGE(PG8_SB(0, 0), b2, voffB); PG8_STAGE(PG8_SB(0, 1), b2 + hstep, voffB); PG8_STAGE(PG8_SA(0, 0), a2, voffA);
;             PG8_WAIT_V(8); PG8_WAIT_L(0); PG8_BAR; PG8_MMA(1, 0, At, B0); PG8_MMA(1, 1, At, B1); PG8_BAR; PG8_SCHED;
;             PG8_LDB(B0, 1, 0); PG8_LDB(B1, 1, 1); PG8_SCHED; PG8_LDA(At, 1, 0); PG8_STAGE(PG8_SA(0, 1), a2 + hstep, voffA);
;             PG8_WAIT_V(8); PG8_WAIT_L(0); PG8_BAR; PG8_MMA(0, 0, At, B0); PG8_MMA(0, 1, At, B1); PG8_BAR; PG8_SCHED;
;             PG8_LDA(At, 1, 1); PG8_STAGE(PG8_SB(1, 0), b3, voffB); PG8_STAGE(PG8_SB(1, 1), b3 + hstep, voffB); PG8_STAGE(PG8_SA(1, 0), a3, voffA);
;             PG8_WAIT_V(8); PG8_WAIT_L(0); PG8_BAR; PG8_MMA(1, 0, At, B0); PG8_MMA(1, 1, At, B1); PG8_BAR; PG8_SCHED;
;     DI void operator()(const pg8::f32x4 (&acc)[2][2][4][2], const pg8::Unit& u, int wr, int wc, int fr, int fq) const {
;     ...
;                 const int row = u.pm * 256 + ai * 128 + wr * 64 + m * 16 + fr; const float rs = rstdx[row];
.LBB0_753:
	s_ashr_i32 s19, s18, 31
	s_lshl_b64 s[20:21], s[18:19], 19
	s_add_u32 s20, s7, s20
	s_addc_u32 s21, s34, s21
	s_and_b64 s[22:23], s[38:39], exec
	s_cselect_b32 s19, s21, s27
	s_cselect_b32 s44, s20, s26
	s_ashr_i32 s17, s16, 31
	s_lshl_b64 s[22:23], s[16:17], 19
	v_readlane_b32 s30, v255, 3
	v_readlane_b32 s31, v255, 4
	s_add_u32 s22, s30, s22
	s_addc_u32 s23, s31, s23
	s_and_b64 s[30:31], s[38:39], exec
	s_cselect_b32 s17, s23, s29
	s_cselect_b32 s45, s22, s28
	s_add_u32 s26, s26, 0x40080
	s_addc_u32 s27, s27, 0
	s_add_u32 s46, s28, 0x100
	s_addc_u32 s47, s29, 0
	s_mov_b32 s48, -2
	s_lshl_b32 s100, s24, 8
	v_add_u32_e32 v173, s100, v144
	v_mov_b32_e32 v250, v173
	v_ashrrev_i32_e32 v251, 31, v250
	v_lshl_add_u64 v[250:251], v[250:251], 2, s[8:9]
	global_load_dword v174, v[250:251], off
	v_add_u32_e32 v232, s100, v146
	v_ashrrev_i32_e32 v233, 31, v232
	v_lshl_add_u64 v[232:233], v[232:233], 2, s[8:9]
	global_load_dword v232, v[232:233], off
	v_add_u32_e32 v238, s100, v147
	v_ashrrev_i32_e32 v239, 31, v238
	v_lshl_add_u64 v[238:239], v[238:239], 2, s[8:9]
	global_load_dword v238, v[238:239], off
	v_add_u32_e32 v242, s100, v148
	v_ashrrev_i32_e32 v243, 31, v242
	v_lshl_add_u64 v[242:243], v[242:243], 2, s[8:9]
	global_load_dword v242, v[242:243], off
	v_add_u32_e32 v244, 0x80, v173
	v_ashrrev_i32_e32 v245, 31, v244
	v_lshl_add_u64 v[244:245], v[244:245], 2, s[8:9]
	global_load_dword v244, v[244:245], off
	v_add_u32_e32 v246, 0x90, v173
	v_ashrrev_i32_e32 v247, 31, v246
	v_lshl_add_u64 v[246:247], v[246:247], 2, s[8:9]
	global_load_dword v246, v[246:247], off
	v_add_u32_e32 v248, 0xa0, v173
	v_ashrrev_i32_e32 v249, 31, v248
	v_lshl_add_u64 v[248:249], v[248:249], 2, s[8:9]
	global_load_dword v248, v[248:249], off
	v_add_u32_e32 v250, 0xb0, v173
	v_ashrrev_i32_e32 v251, 31, v250
	v_lshl_add_u64 v[250:251], v[250:251], 2, s[8:9]
	global_load_dword v250, v[250:251], off
	s_add_u32 s28, s26, 0xfffc0080
	s_addc_u32 s29, s27, -1
	s_add_i32 s49, 0, 0x10000
	s_cmp_eq_u32 s48, 12
	s_cselect_b32 s31, s19, s29
	s_cselect_b32 s30, s44, s28
	v_add_u32_e32 v142, s49, v145
	s_cselect_b32 s29, s17, s47
	s_cselect_b32 s28, s45, s46
	s_add_i32 s52, 0, 0x14000
	ds_read_b128 v[150:153], v142
	ds_read_b128 v[154:157], v142 offset:1024
	ds_read_b128 v[158:161], v142 offset:2048
	ds_read_b128 v[162:165], v142 offset:3072
	v_add_u32_e32 v142, s52, v145
	ds_read_b128 v[166:169], v142
	ds_read_b128 v[176:179], v142 offset:1024
	ds_read_b128 v[180:183], v142 offset:2048
	ds_read_b128 v[184:187], v142 offset:3072
	s_add_i32 m0, s35, 0xc000
	ds_read_b128 v[188:191], v149
	ds_read_b128 v[192:195], v149 offset:1024
	ds_read_b128 v[196:199], v149 offset:2048
	ds_read_b128 v[200:203], v149 offset:3072
	ds_read_b128 v[204:207], v149 offset:4096
	ds_read_b128 v[208:211], v149 offset:5120
	ds_read_b128 v[212:215], v149 offset:6144
	ds_read_b128 v[216:219], v149 offset:7168
	global_load_lds_dwordx4 v138, s[26:27]
	s_add_i32 m0, s35, 0xe000
	s_nop 0
	global_load_lds_dwordx4 v140, s[26:27]
	s_waitcnt vmcnt(8)
	s_waitcnt lgkmcnt(0)
	s_barrier
	s_setprio 1
	s_waitcnt lgkmcnt(0)
	v_mfma_f32_16x16x32_bf16 v[126:129], v[150:153], v[188:191], 0
	v_mfma_f32_16x16x32_bf16 v[122:125], v[158:161], v[188:191], 0
	v_mfma_f32_16x16x32_bf16 v[110:113], v[150:153], v[196:199], 0
	v_mfma_f32_16x16x32_bf16 v[106:109], v[158:161], v[196:199], 0
	v_mfma_f32_16x16x32_bf16 v[94:97], v[150:153], v[204:207], 0
	v_mfma_f32_16x16x32_bf16 v[90:93], v[158:161], v[204:207], 0
	v_mfma_f32_16x16x32_bf16 v[78:81], v[150:153], v[212:215], 0
	v_mfma_f32_16x16x32_bf16 v[74:77], v[158:161], v[212:215], 0
	v_mfma_f32_16x16x32_bf16 v[126:129], v[154:157], v[192:195], v[126:129]
	v_mfma_f32_16x16x32_bf16 v[122:125], v[162:165], v[192:195], v[122:125]
	v_mfma_f32_16x16x32_bf16 v[110:113], v[154:157], v[200:203], v[110:113]
	v_mfma_f32_16x16x32_bf16 v[106:109], v[162:165], v[200:203], v[106:109]
	v_mfma_f32_16x16x32_bf16 v[94:97], v[154:157], v[208:211], v[94:97]
	v_mfma_f32_16x16x32_bf16 v[90:93], v[162:165], v[208:211], v[90:93]
	v_mfma_f32_16x16x32_bf16 v[78:81], v[154:157], v[216:219], v[78:81]
	v_mfma_f32_16x16x32_bf16 v[74:77], v[162:165], v[216:219], v[74:77]
	v_mfma_f32_16x16x32_bf16 v[118:121], v[166:169], v[188:191], 0
	v_mfma_f32_16x16x32_bf16 v[114:117], v[180:183], v[188:191], 0
	v_mfma_f32_16x16x32_bf16 v[102:105], v[166:169], v[196:199], 0
	v_mfma_f32_16x16x32_bf16 v[98:101], v[180:183], v[196:199], 0
	v_mfma_f32_16x16x32_bf16 v[86:89], v[166:169], v[204:207], 0
	v_mfma_f32_16x16x32_bf16 v[82:85], v[180:183], v[204:207], 0
	v_mfma_f32_16x16x32_bf16 v[70:73], v[166:169], v[212:215], 0
	v_mfma_f32_16x16x32_bf16 v[66:69], v[180:183], v[212:215], 0
	v_mfma_f32_16x16x32_bf16 v[118:121], v[176:179], v[192:195], v[118:121]
	v_mfma_f32_16x16x32_bf16 v[114:117], v[184:187], v[192:195], v[114:117]
	v_mfma_f32_16x16x32_bf16 v[102:105], v[176:179], v[200:203], v[102:105]
	v_mfma_f32_16x16x32_bf16 v[98:101], v[184:187], v[200:203], v[98:101]
	v_mfma_f32_16x16x32_bf16 v[86:89], v[176:179], v[208:211], v[86:89]
	v_mfma_f32_16x16x32_bf16 v[82:85], v[184:187], v[208:211], v[82:85]
	v_mfma_f32_16x16x32_bf16 v[70:73], v[176:179], v[216:219], v[70:73]
	v_mfma_f32_16x16x32_bf16 v[66:69], v[184:187], v[216:219], v[66:69]
	s_setprio 0
	s_barrier
; #define PG8_STAGE(bufoff, gbase, voff) do { _Pragma("unroll") for (int _i = 0; _i < 2; ++_i) \
;         __builtin_amdgcn_global_load_lds((const unsigned*)((const char*)(gbase) + (voff)[_i]), (PG8_LAS unsigned*)(lds + (bufoff) + ldsw + _i * 8192), 16, 0, 0); } while (0)
; #define PG8_LDA(dst, b, h) do { _Pragma("unroll") for (int m = 0; m < 4; ++m) _Pragma("unroll") for (int k = 0; k < 2; ++k) dst[m][k] = *(const PG8_LAS bf16x8*)(lds + PG8_SA(b, h) + aoff + m * 2048 + k * 1024); } while (0)
; #define PG8_LDB(dst, b, h) do { _Pragma("unroll") for (int n = 0; n < 2; ++n) _Pragma("unroll") for (int k = 0; k < 2; ++k) dst[n][k] = *(const PG8_LAS bf16x8*)(lds + PG8_SB(b, h) + boff + n * 2048 + k * 1024); } while (0)
; #define PG8_MMA(ai, bj, At, Bt) do { __builtin_amdgcn_s_setprio(1); _Pragma("unroll") for (int m = 0; m < 4; ++m) _Pragma("unroll") for (int n = 0; n < 2; ++n) _Pragma("unroll") for (int k = 0; k < 2; ++k) \
;         acc[ai][bj][m][n] = __builtin_amdgcn_mfma_f32_16x16x32_bf16(Bt[n][k], At[m][k], acc[ai][bj][m][n], 0, 0, 0); __builtin_amdgcn_s_setprio(0); } while (0)
; #define PG8_WAIT_V(n) asm volatile("s_waitcnt vmcnt(" #n ")" ::: "memory")
; #define PG8_WAIT_L(n) asm volatile("s_waitcnt lgkmcnt(" #n ")" ::: "memory")
; #define PG8_BAR __builtin_amdgcn_s_barrier()
; #define PG8_SCHED __builtin_amdgcn_sched_barrier(0)
; template <class Epi, class Sched, bool ALIGN_EPI = false, bool SP2 = false>
; __device__ __forceinline__ void gemm_phase(PG8_LAS unsigned char* lds, const Gemm g, const Sched& S, const Epi& E, int tid_in) {
;     ...
;             PG8_WAIT_V(8); PG8_WAIT_L(0); PG8_BAR; PG8_MMA(0, 0, At, B0); PG8_MMA(0, 1, At, B1); PG8_BAR; PG8_SCHED;
;             PG8_LDA(At, 0, 1); PG8_STAGE(PG8_SB(0, 0), b2, voffB); PG8_STAGE(PG8_SB(0, 1), b2 + hstep, voffB); PG8_STAGE(PG8_SA(0, 0), a2, voffA);
;             PG8_WAIT_V(8); PG8_WAIT_L(0); PG8_BAR; PG8_MMA(1, 0, At, B0); PG8_MMA(1, 1, At, B1); PG8_BAR; PG8_SCHED;
;             PG8_LDB(B0, 1, 0); PG8_LDB(B1, 1, 1); PG8_SCHED; PG8_LDA(At, 1, 0); PG8_STAGE(PG8_SA(0, 1), a2 + hstep, voffA);
;             PG8_WAIT_V(8); PG8_WAIT_L(0); PG8_BAR; PG8_MMA(0, 0, At, B0); PG8_MMA(0, 1, At, B1); PG8_BAR; PG8_SCHED;
	s_add_i32 s49, s49, s6
	v_lshl_add_u64 v[142:143], s[28:29], 0, v[132:133]
	s_mov_b32 m0, s49
	ds_read_b128 v[188:191], v149 offset:16384
	ds_read_b128 v[192:195], v149 offset:17408
	ds_read_b128 v[196:199], v149 offset:18432
	ds_read_b128 v[200:203], v149 offset:19456
	ds_read_b128 v[204:207], v149 offset:20480
	ds_read_b128 v[208:211], v149 offset:21504
	ds_read_b128 v[212:215], v149 offset:22528
	ds_read_b128 v[216:219], v149 offset:23552
	global_load_lds_dwordx4 v132, s[28:29]
	s_add_i32 m0, s49, 0x2000
	s_add_u32 s50, s28, 0x40000
	v_lshl_add_u64 v[170:171], s[28:29], 0, v[136:137]
	s_addc_u32 s51, s29, 0
	s_add_i32 s49, s52, s6
	global_load_lds_dwordx4 v136, s[28:29]
	s_mov_b32 m0, s49
	v_lshl_add_u64 v[222:223], s[30:31], 0, v[134:135]
	global_load_lds_dwordx4 v132, s[50:51]
	s_add_i32 m0, s49, 0x2000
	s_nop 0
	global_load_lds_dwordx4 v136, s[50:51]
	v_lshl_add_u64 v[220:221], s[30:31], 0, v[130:131]
	s_mov_b32 m0, s35
	s_nop 0
	global_load_lds_dwordx4 v130, s[30:31]
	s_mov_b32 m0, s36
	s_nop 0
	global_load_lds_dwordx4 v134, s[30:31]
	s_waitcnt vmcnt(8)
	s_waitcnt lgkmcnt(0)
	s_barrier
	s_setprio 1
	s_waitcnt lgkmcnt(0)
	v_mfma_f32_16x16x32_bf16 v[60:63], v[150:153], v[188:191], 0
	v_mfma_f32_16x16x32_bf16 v[56:59], v[158:161], v[188:191], 0
	v_mfma_f32_16x16x32_bf16 v[44:47], v[150:153], v[196:199], 0
	v_mfma_f32_16x16x32_bf16 v[40:43], v[158:161], v[196:199], 0
	v_mfma_f32_16x16x32_bf16 v[28:31], v[150:153], v[204:207], 0
	v_mfma_f32_16x16x32_bf16 v[24:27], v[158:161], v[204:207], 0
	v_mfma_f32_16x16x32_bf16 v[12:15], v[150:153], v[212:215], 0
	v_mfma_f32_16x16x32_bf16 v[8:11], v[158:161], v[212:215], 0
	v_mfma_f32_16x16x32_bf16 v[60:63], v[154:157], v[192:195], v[60:63]
	v_mfma_f32_16x16x32_bf16 v[56:59], v[162:165], v[192:195], v[56:59]
	v_mfma_f32_16x16x32_bf16 v[44:47], v[154:157], v[200:203], v[44:47]
	v_mfma_f32_16x16x32_bf16 v[40:43], v[162:165], v[200:203], v[40:43]
	v_mfma_f32_16x16x32_bf16 v[28:31], v[154:157], v[208:211], v[28:31]
	v_mfma_f32_16x16x32_bf16 v[24:27], v[162:165], v[208:211], v[24:27]
	v_mfma_f32_16x16x32_bf16 v[12:15], v[154:157], v[216:219], v[12:15]
	v_mfma_f32_16x16x32_bf16 v[8:11], v[162:165], v[216:219], v[8:11]
	v_mfma_f32_16x16x32_bf16 v[52:55], v[166:169], v[188:191], 0
	v_mfma_f32_16x16x32_bf16 v[48:51], v[180:183], v[188:191], 0
	v_mfma_f32_16x16x32_bf16 v[36:39], v[166:169], v[196:199], 0
	v_mfma_f32_16x16x32_bf16 v[32:35], v[180:183], v[196:199], 0
	v_mfma_f32_16x16x32_bf16 v[20:23], v[166:169], v[204:207], 0
	v_mfma_f32_16x16x32_bf16 v[16:19], v[180:183], v[204:207], 0
	v_mfma_f32_16x16x32_bf16 v[4:7], v[166:169], v[212:215], 0
	v_mfma_f32_16x16x32_bf16 v[0:3], v[180:183], v[212:215], 0
	v_mfma_f32_16x16x32_bf16 v[52:55], v[176:179], v[192:195], v[52:55]
	v_mfma_f32_16x16x32_bf16 v[48:51], v[184:187], v[192:195], v[48:51]
	v_mfma_f32_16x16x32_bf16 v[36:39], v[176:179], v[200:203], v[36:39]
	v_mfma_f32_16x16x32_bf16 v[32:35], v[184:187], v[200:203], v[32:35]
	v_mfma_f32_16x16x32_bf16 v[20:23], v[176:179], v[208:211], v[20:23]
	v_mfma_f32_16x16x32_bf16 v[16:19], v[184:187], v[208:211], v[16:19]
	v_mfma_f32_16x16x32_bf16 v[4:7], v[176:179], v[216:219], v[4:7]
	v_mfma_f32_16x16x32_bf16 v[0:3], v[184:187], v[216:219], v[0:3]
	s_setprio 0
	s_barrier
	s_add_i32 s49, 0, 0x18000
	s_add_i32 s50, 0, 0x1c000
	v_add_u32_e32 v162, s49, v145
	v_add_u32_e32 v172, s50, v145
	ds_read_b128 v[150:153], v162
	ds_read_b128 v[154:157], v162 offset:1024
	ds_read_b128 v[158:161], v162 offset:2048
	ds_read_b128 v[162:165], v162 offset:3072
	ds_read_b128 v[166:169], v172
	ds_read_b128 v[176:179], v172 offset:1024
	ds_read_b128 v[180:183], v172 offset:2048
	ds_read_b128 v[184:187], v172 offset:3072
	s_add_u32 s30, s30, 0x40000
	s_addc_u32 s31, s31, 0
	s_mov_b32 m0, s37
	ds_read_b128 v[188:191], v149 offset:32768
	ds_read_b128 v[192:195], v149 offset:33792
	ds_read_b128 v[196:199], v149 offset:34816
	ds_read_b128 v[200:203], v149 offset:35840
	ds_read_b128 v[204:207], v149 offset:36864
	ds_read_b128 v[208:211], v149 offset:37888
	ds_read_b128 v[212:215], v149 offset:38912
	ds_read_b128 v[216:219], v149 offset:39936
	global_load_lds_dwordx4 v130, s[30:31]
	s_mov_b32 m0, s40
	s_nop 0
	global_load_lds_dwordx4 v134, s[30:31]
	s_waitcnt vmcnt(8)
	s_waitcnt lgkmcnt(0)
	s_barrier
; #define PG8_STAGE(bufoff, gbase, voff) do { _Pragma("unroll") for (int _i = 0; _i < 2; ++_i) \
;         __builtin_amdgcn_global_load_lds((const unsigned*)((const char*)(gbase) + (voff)[_i]), (PG8_LAS unsigned*)(lds + (bufoff) + ldsw + _i * 8192), 16, 0, 0); } while (0)
; #define PG8_LDA(dst, b, h) do { _Pragma("unroll") for (int m = 0; m < 4; ++m) _Pragma("unroll") for (int k = 0; k < 2; ++k) dst[m][k] = *(const PG8_LAS bf16x8*)(lds + PG8_SA(b, h) + aoff + m * 2048 + k * 1024); } while (0)
; #define PG8_MMA(ai, bj, At, Bt) do { __builtin_amdgcn_s_setprio(1); _Pragma("unroll") for (int m = 0; m < 4; ++m) _Pragma("unroll") for (int n = 0; n < 2; ++n) _Pragma("unroll") for (int k = 0; k < 2; ++k) \
;         acc[ai][bj][m][n] = __builtin_amdgcn_mfma_f32_16x16x32_bf16(Bt[n][k], At[m][k], acc[ai][bj][m][n], 0, 0, 0); __builtin_amdgcn_s_setprio(0); } while (0)
; #define PG8_WAIT_V(n) asm volatile("s_waitcnt vmcnt(" #n ")" ::: "memory")
; #define PG8_WAIT_L(n) asm volatile("s_waitcnt lgkmcnt(" #n ")" ::: "memory")
; #define PG8_BAR __builtin_amdgcn_s_barrier()
; #define PG8_SCHED __builtin_amdgcn_sched_barrier(0)
; template <class Epi, class Sched, bool ALIGN_EPI = false, bool SP2 = false>
; __device__ __forceinline__ void gemm_phase(PG8_LAS unsigned char* lds, const Gemm g, const Sched& S, const Epi& E, int tid_in) {
;     ...
;             PG8_WAIT_V(8); PG8_WAIT_L(0); PG8_BAR; PG8_MMA(0, 0, At, B0); PG8_MMA(0, 1, At, B1); PG8_BAR; PG8_SCHED;
;             PG8_LDA(At, 1, 1); PG8_STAGE(PG8_SB(1, 0), b3, voffB); PG8_STAGE(PG8_SB(1, 1), b3 + hstep, voffB); PG8_STAGE(PG8_SA(1, 0), a3, voffA);
;             PG8_WAIT_V(8); PG8_WAIT_L(0); PG8_BAR; PG8_MMA(1, 0, At, B0); PG8_MMA(1, 1, At, B1); PG8_BAR; PG8_SCHED;
	s_setprio 1
	s_waitcnt lgkmcnt(0)
	v_mfma_f32_16x16x32_bf16 v[126:129], v[150:153], v[188:191], v[126:129]
	v_mfma_f32_16x16x32_bf16 v[122:125], v[158:161], v[188:191], v[122:125]
	v_mfma_f32_16x16x32_bf16 v[110:113], v[150:153], v[196:199], v[110:113]
	v_mfma_f32_16x16x32_bf16 v[106:109], v[158:161], v[196:199], v[106:109]
	v_mfma_f32_16x16x32_bf16 v[94:97], v[150:153], v[204:207], v[94:97]
	v_mfma_f32_16x16x32_bf16 v[90:93], v[158:161], v[204:207], v[90:93]
	v_mfma_f32_16x16x32_bf16 v[78:81], v[150:153], v[212:215], v[78:81]
	v_mfma_f32_16x16x32_bf16 v[74:77], v[158:161], v[212:215], v[74:77]
	v_mfma_f32_16x16x32_bf16 v[126:129], v[154:157], v[192:195], v[126:129]
	v_mfma_f32_16x16x32_bf16 v[122:125], v[162:165], v[192:195], v[122:125]
	v_mfma_f32_16x16x32_bf16 v[110:113], v[154:157], v[200:203], v[110:113]
	v_mfma_f32_16x16x32_bf16 v[106:109], v[162:165], v[200:203], v[106:109]
	v_mfma_f32_16x16x32_bf16 v[94:97], v[154:157], v[208:211], v[94:97]
	v_mfma_f32_16x16x32_bf16 v[90:93], v[162:165], v[208:211], v[90:93]
	v_mfma_f32_16x16x32_bf16 v[78:81], v[154:157], v[216:219], v[78:81]
	v_mfma_f32_16x16x32_bf16 v[74:77], v[162:165], v[216:219], v[74:77]
	v_mfma_f32_16x16x32_bf16 v[118:121], v[166:169], v[188:191], v[118:121]
	v_mfma_f32_16x16x32_bf16 v[114:117], v[180:183], v[188:191], v[114:117]
	v_mfma_f32_16x16x32_bf16 v[102:105], v[166:169], v[196:199], v[102:105]
	v_mfma_f32_16x16x32_bf16 v[98:101], v[180:183], v[196:199], v[98:101]
	v_mfma_f32_16x16x32_bf16 v[86:89], v[166:169], v[204:207], v[86:89]
	v_mfma_f32_16x16x32_bf16 v[82:85], v[180:183], v[204:207], v[82:85]
	v_mfma_f32_16x16x32_bf16 v[70:73], v[166:169], v[212:215], v[70:73]
	v_mfma_f32_16x16x32_bf16 v[66:69], v[180:183], v[212:215], v[66:69]
	v_mfma_f32_16x16x32_bf16 v[118:121], v[176:179], v[192:195], v[118:121]
	v_mfma_f32_16x16x32_bf16 v[114:117], v[184:187], v[192:195], v[114:117]
	v_mfma_f32_16x16x32_bf16 v[102:105], v[176:179], v[200:203], v[102:105]
	v_mfma_f32_16x16x32_bf16 v[98:101], v[184:187], v[200:203], v[98:101]
	v_mfma_f32_16x16x32_bf16 v[86:89], v[176:179], v[208:211], v[86:89]
	v_mfma_f32_16x16x32_bf16 v[82:85], v[184:187], v[208:211], v[82:85]
	v_mfma_f32_16x16x32_bf16 v[70:73], v[176:179], v[216:219], v[70:73]
	v_mfma_f32_16x16x32_bf16 v[66:69], v[184:187], v[216:219], v[66:69]
	s_setprio 0
	s_barrier
	s_add_i32 s30, s49, s6
	s_mov_b32 m0, s30
	ds_read_b128 v[188:191], v149 offset:49152
	ds_read_b128 v[192:195], v149 offset:50176
	ds_read_b128 v[196:199], v149 offset:51200
	ds_read_b128 v[200:203], v149 offset:52224
	ds_read_b128 v[204:207], v149 offset:53248
	ds_read_b128 v[208:211], v149 offset:54272
	ds_read_b128 v[212:215], v149 offset:55296
	ds_read_b128 v[216:219], v149 offset:56320
	s_add_u32 s98, s28, 0x80
	s_addc_u32 s99, s29, 0
	global_load_lds_dwordx4 v132, s[98:99]
	s_add_i32 m0, s30, 0x2000
	s_add_u32 s28, s28, 0x40080
	v_lshl_add_u64 v[142:143], v[170:171], 0, s[92:93]
	s_addc_u32 s29, s29, 0
	s_add_i32 s30, s50, s6
	global_load_lds_dwordx4 v[142:143], off
	s_mov_b32 m0, s30
	s_nop 0
	global_load_lds_dwordx4 v132, s[28:29]
	s_add_i32 m0, s30, 0x2000
	s_nop 0
	global_load_lds_dwordx4 v136, s[28:29]
	v_lshl_add_u64 v[142:143], v[220:221], 0, s[92:93]
	s_mov_b32 m0, s41
	s_nop 0
	global_load_lds_dwordx4 v[142:143], off
	v_lshl_add_u64 v[142:143], v[222:223], 0, s[92:93]
	s_mov_b32 m0, s42
	s_nop 0
	global_load_lds_dwordx4 v[142:143], off
	s_waitcnt vmcnt(8)
	s_waitcnt lgkmcnt(0)
	s_barrier
	s_setprio 1
	s_waitcnt lgkmcnt(0)
	v_mfma_f32_16x16x32_bf16 v[60:63], v[150:153], v[188:191], v[60:63]
	v_mfma_f32_16x16x32_bf16 v[56:59], v[158:161], v[188:191], v[56:59]
	v_mfma_f32_16x16x32_bf16 v[44:47], v[150:153], v[196:199], v[44:47]
	v_mfma_f32_16x16x32_bf16 v[40:43], v[158:161], v[196:199], v[40:43]
	v_mfma_f32_16x16x32_bf16 v[28:31], v[150:153], v[204:207], v[28:31]
	v_mfma_f32_16x16x32_bf16 v[24:27], v[158:161], v[204:207], v[24:27]
	v_mfma_f32_16x16x32_bf16 v[12:15], v[150:153], v[212:215], v[12:15]
	v_mfma_f32_16x16x32_bf16 v[8:11], v[158:161], v[212:215], v[8:11]
	v_mfma_f32_16x16x32_bf16 v[60:63], v[154:157], v[192:195], v[60:63]
	v_mfma_f32_16x16x32_bf16 v[56:59], v[162:165], v[192:195], v[56:59]
	v_mfma_f32_16x16x32_bf16 v[44:47], v[154:157], v[200:203], v[44:47]
	v_mfma_f32_16x16x32_bf16 v[40:43], v[162:165], v[200:203], v[40:43]
	v_mfma_f32_16x16x32_bf16 v[28:31], v[154:157], v[208:211], v[28:31]
	v_mfma_f32_16x16x32_bf16 v[24:27], v[162:165], v[208:211], v[24:27]
	v_mfma_f32_16x16x32_bf16 v[12:15], v[154:157], v[216:219], v[12:15]
	v_mfma_f32_16x16x32_bf16 v[8:11], v[162:165], v[216:219], v[8:11]
	v_mfma_f32_16x16x32_bf16 v[52:55], v[166:169], v[188:191], v[52:55]
	v_mfma_f32_16x16x32_bf16 v[48:51], v[180:183], v[188:191], v[48:51]
	v_mfma_f32_16x16x32_bf16 v[36:39], v[166:169], v[196:199], v[36:39]
	v_mfma_f32_16x16x32_bf16 v[32:35], v[180:183], v[196:199], v[32:35]
	v_mfma_f32_16x16x32_bf16 v[20:23], v[166:169], v[204:207], v[20:23]
	v_mfma_f32_16x16x32_bf16 v[16:19], v[180:183], v[204:207], v[16:19]
	v_mfma_f32_16x16x32_bf16 v[4:7], v[166:169], v[212:215], v[4:7]
	v_mfma_f32_16x16x32_bf16 v[0:3], v[180:183], v[212:215], v[0:3]
	v_mfma_f32_16x16x32_bf16 v[52:55], v[176:179], v[192:195], v[52:55]
	v_mfma_f32_16x16x32_bf16 v[48:51], v[184:187], v[192:195], v[48:51]
	v_mfma_f32_16x16x32_bf16 v[36:39], v[176:179], v[200:203], v[36:39]
	v_mfma_f32_16x16x32_bf16 v[32:35], v[184:187], v[200:203], v[32:35]
	v_mfma_f32_16x16x32_bf16 v[20:23], v[176:179], v[208:211], v[20:23]
	v_mfma_f32_16x16x32_bf16 v[16:19], v[184:187], v[208:211], v[16:19]
	v_mfma_f32_16x16x32_bf16 v[4:7], v[176:179], v[216:219], v[4:7]
	v_mfma_f32_16x16x32_bf16 v[0:3], v[184:187], v[216:219], v[0:3]
	s_setprio 0
	s_barrier
	s_add_i32 s48, s48, 2
	s_add_u32 s26, s26, 0x100
	s_addc_u32 s27, s27, 0
	s_add_u32 s46, s46, 0x100
	s_addc_u32 s47, s47, 0
	s_cmp_gt_u32 s48, 13
	s_cbranch_scc0 .LBB0_754
	s_branch .Lpeel_exit_0
	.p2align	6
